# batched retention-state loads in the retention-output phase; pipelined residual epilogue (12 loads in flight, counted vmcnt) in out-proj and ffn-out GEMMs
# speedup vs baseline: 1.0138x; 1.0125x over previous
; #define LAS __attribute__((address_space(3)))
; __device__ __forceinline__ unsigned cvt_pk_bf16(float lo, float hi) { unsigned r; asm volatile("v_cvt_pk_bf16_f32 %0, %1, %2" : "=v"(r) : "v"(lo), "v"(hi)); return r; }
;     __device__ __forceinline__ void operator()(const f32x4 (&acc)[2][2][4][2], const pg8::Unit& u, int wr, int wc, int fr, int fq, LAS unsigned char*) const {
;         const int row0 = u.pm * 256 + wr * 64 + fr, col0 = u.pn * 256 + wc * 32 + 4 * fq;
; #pragma unroll
;         for (int ai = 0; ai < 2; ++ai)
; #pragma unroll
;             for (int m = 0; m < 4; ++m) {
;                 const int row = row0 + ai * 128 + m * 16; const size_t off = (size_t)row * DM + col0; float q = 0.f;
; #pragma unroll
;                 for (int bj = 0; bj < 2; ++bj)
; #pragma unroll
;                     for (int n = 0; n < 2; ++n) { const size_t o = off + bj * 128 + n * 16; const f32x4 xv = *(const f32x4*)(xin + o) + acc[ai][bj][m][n]; *(f32x4*)(xout + o) = xv;
;                         q += (xv[0] * xv[0] + xv[1] * xv[1]) + (xv[2] * xv[2] + xv[3] * xv[3]);
;                         u32x2 w; w.x = cvt_pk_bf16(xv[0], xv[1]); w.y = cvt_pk_bf16(xv[2], xv[3]); *(u32x2*)(xb + o) = w; }
;                 q += __shfl_xor(q, 16); q += __shfl_xor(q, 32);
;                 if (fq == 0) ssq[(size_t)row * 16 + u.pn * 4 + wc] = q;
;             }
.LBB0_64:
	v_lshl_add_u32 v136, s62, 8, v142
	v_lshl_or_b32 v137, s60, 8, v144
	s_lshl_b32 s26, s60, 4
	s_lshl_b32 s27, s81, 2
	s_add_u32 s26, s26, s27
	v_lshl_add_u32 v139, v136, 10, v137
	v_lshl_add_u32 v140, v136, 6, s26
	v_lshlrev_b32_e32 v138, 2, v139
	v_lshlrev_b32_e32 v139, 1, v139
	v_xor_b32_e32 v141, 16, v187
	v_xor_b32_e32 v172, 32, v187
	v_lshlrev_b32_e32 v141, 2, v141
	v_lshlrev_b32_e32 v172, 2, v172
	global_load_dwordx4 v[198:201], v138, s[18:19]
	global_load_dwordx4 v[202:205], v138, s[18:19] offset:64
	global_load_dwordx4 v[206:209], v138, s[18:19] offset:512
	global_load_dwordx4 v[210:213], v138, s[18:19] offset:576
	v_add_u32_e32 v173, 0x10000, v138
	global_load_dwordx4 v[214:217], v173, s[18:19]
	global_load_dwordx4 v[218:221], v173, s[18:19] offset:64
	global_load_dwordx4 v[222:225], v173, s[18:19] offset:512
	global_load_dwordx4 v[226:229], v173, s[18:19] offset:576
	v_add_u32_e32 v173, 0x20000, v138
	global_load_dwordx4 v[156:159], v173, s[18:19]
	global_load_dwordx4 v[160:163], v173, s[18:19] offset:64
	global_load_dwordx4 v[164:167], v173, s[18:19] offset:512
	global_load_dwordx4 v[168:171], v173, s[18:19] offset:576
	v_mov_b32_e32 v174, v138
	v_mov_b32_e32 v175, v139
	v_mov_b32_e32 v176, v140
	s_waitcnt vmcnt(11)
	v_pk_add_f32 v[200:201], v[128:129], v[200:201]
	v_pk_add_f32 v[198:199], v[126:127], v[198:199]
	global_store_dwordx4 v174, v[198:201], s[12:13]
	v_mul_f32_e32 v178, v201, v201
	v_mul_f32_e32 v177, v199, v199
	v_fmac_f32_e32 v177, v198, v198
	v_fmac_f32_e32 v178, v200, v200
	v_cvt_pk_bf16_f32 v180, v198, v199
	v_cvt_pk_bf16_f32 v181, v200, v201
	v_add_f32_e32 v179, v177, v178
	global_store_dwordx2 v175, v[180:181], s[48:49]
	s_waitcnt vmcnt(12)
	v_pk_add_f32 v[204:205], v[124:125], v[204:205]
	v_pk_add_f32 v[202:203], v[122:123], v[202:203]
	global_store_dwordx4 v174, v[202:205], s[12:13] offset:64
	v_mul_f32_e32 v178, v205, v205
	v_mul_f32_e32 v177, v203, v203
	v_fmac_f32_e32 v177, v202, v202
	v_fmac_f32_e32 v178, v204, v204
	v_cvt_pk_bf16_f32 v182, v202, v203
	v_cvt_pk_bf16_f32 v183, v204, v205
	v_add_f32_e32 v177, v177, v178
	v_add_f32_e32 v179, v179, v177
	global_store_dwordx2 v175, v[182:183], s[48:49] offset:32
	s_waitcnt vmcnt(13)
	v_pk_add_f32 v[208:209], v[120:121], v[208:209]
	v_pk_add_f32 v[206:207], v[118:119], v[206:207]
	global_store_dwordx4 v174, v[206:209], s[12:13] offset:512
	v_mul_f32_e32 v178, v209, v209
	v_mul_f32_e32 v177, v207, v207
	v_fmac_f32_e32 v177, v206, v206
	v_fmac_f32_e32 v178, v208, v208
	v_cvt_pk_bf16_f32 v180, v206, v207
	v_cvt_pk_bf16_f32 v181, v208, v209
	v_add_f32_e32 v177, v177, v178
	v_add_f32_e32 v179, v179, v177
	global_store_dwordx2 v175, v[180:181], s[48:49] offset:256
	s_waitcnt vmcnt(14)
	v_pk_add_f32 v[212:213], v[116:117], v[212:213]
	v_pk_add_f32 v[210:211], v[114:115], v[210:211]
	global_store_dwordx4 v174, v[210:213], s[12:13] offset:576
	v_mul_f32_e32 v178, v213, v213
	v_mul_f32_e32 v177, v211, v211
	v_fmac_f32_e32 v177, v210, v210
	v_fmac_f32_e32 v178, v212, v212
	v_cvt_pk_bf16_f32 v182, v210, v211
	v_cvt_pk_bf16_f32 v183, v212, v213
	v_add_f32_e32 v177, v177, v178
	v_add_f32_e32 v179, v179, v177
	global_store_dwordx2 v175, v[182:183], s[48:49] offset:288
	ds_bpermute_b32 v177, v141, v179
	s_waitcnt lgkmcnt(0)
	v_add_f32_e32 v179, v179, v177
	ds_bpermute_b32 v178, v172, v179
	s_waitcnt lgkmcnt(0)
	v_add_f32_e32 v179, v179, v178
	s_and_saveexec_b64 s[62:63], s[4:5]
	global_store_dword v176, v179, s[14:15]
	s_mov_b64 exec, s[62:63]
	v_add_u32_e32 v173, 0x30000, v138
	global_load_dwordx4 v[198:201], v173, s[18:19]
	global_load_dwordx4 v[202:205], v173, s[18:19] offset:64
	global_load_dwordx4 v[206:209], v173, s[18:19] offset:512
	global_load_dwordx4 v[210:213], v173, s[18:19] offset:576
	v_add_u32_e32 v174, 0x10000, v138
	v_add_u32_e32 v175, 0x8000, v139
	v_add_u32_e32 v176, 0x400, v140
	s_waitcnt vmcnt(20)
	v_pk_add_f32 v[216:217], v[112:113], v[216:217]
	v_pk_add_f32 v[214:215], v[110:111], v[214:215]
	global_store_dwordx4 v174, v[214:217], s[12:13]
	v_mul_f32_e32 v178, v217, v217
	v_mul_f32_e32 v177, v215, v215
	v_fmac_f32_e32 v177, v214, v214
	v_fmac_f32_e32 v178, v216, v216
	v_cvt_pk_bf16_f32 v180, v214, v215
	v_cvt_pk_bf16_f32 v181, v216, v217
	v_add_f32_e32 v179, v177, v178
	global_store_dwordx2 v175, v[180:181], s[48:49]
	s_waitcnt vmcnt(21)
	v_pk_add_f32 v[220:221], v[108:109], v[220:221]
	v_pk_add_f32 v[218:219], v[106:107], v[218:219]
	global_store_dwordx4 v174, v[218:221], s[12:13] offset:64
	v_mul_f32_e32 v178, v221, v221
	v_mul_f32_e32 v177, v219, v219
	v_fmac_f32_e32 v177, v218, v218
	v_fmac_f32_e32 v178, v220, v220
	v_cvt_pk_bf16_f32 v182, v218, v219
	v_cvt_pk_bf16_f32 v183, v220, v221
	v_add_f32_e32 v177, v177, v178
	v_add_f32_e32 v179, v179, v177
	global_store_dwordx2 v175, v[182:183], s[48:49] offset:32
	s_waitcnt vmcnt(22)
	v_pk_add_f32 v[224:225], v[104:105], v[224:225]
	v_pk_add_f32 v[222:223], v[102:103], v[222:223]
	global_store_dwordx4 v174, v[222:225], s[12:13] offset:512
	v_mul_f32_e32 v178, v225, v225
	v_mul_f32_e32 v177, v223, v223
	v_fmac_f32_e32 v177, v222, v222
	v_fmac_f32_e32 v178, v224, v224
	v_cvt_pk_bf16_f32 v180, v222, v223
	v_cvt_pk_bf16_f32 v181, v224, v225
	v_add_f32_e32 v177, v177, v178
	v_add_f32_e32 v179, v179, v177
	global_store_dwordx2 v175, v[180:181], s[48:49] offset:256
	s_waitcnt vmcnt(23)
	v_pk_add_f32 v[228:229], v[100:101], v[228:229]
	v_pk_add_f32 v[226:227], v[98:99], v[226:227]
	global_store_dwordx4 v174, v[226:229], s[12:13] offset:576
	v_mul_f32_e32 v178, v229, v229
	v_mul_f32_e32 v177, v227, v227
	v_fmac_f32_e32 v177, v226, v226
	v_fmac_f32_e32 v178, v228, v228
	v_cvt_pk_bf16_f32 v182, v226, v227
	v_cvt_pk_bf16_f32 v183, v228, v229
	v_add_f32_e32 v177, v177, v178
	v_add_f32_e32 v179, v179, v177
	global_store_dwordx2 v175, v[182:183], s[48:49] offset:288
	ds_bpermute_b32 v177, v141, v179
	s_waitcnt lgkmcnt(0)
; #define LAS __attribute__((address_space(3)))
; __device__ __forceinline__ unsigned cvt_pk_bf16(float lo, float hi) { unsigned r; asm volatile("v_cvt_pk_bf16_f32 %0, %1, %2" : "=v"(r) : "v"(lo), "v"(hi)); return r; }
;     __device__ __forceinline__ void operator()(const f32x4 (&acc)[2][2][4][2], const pg8::Unit& u, int wr, int wc, int fr, int fq, LAS unsigned char*) const {
;         const int row0 = u.pm * 256 + wr * 64 + fr, col0 = u.pn * 256 + wc * 32 + 4 * fq;
; #pragma unroll
;         for (int ai = 0; ai < 2; ++ai)
; #pragma unroll
;             for (int m = 0; m < 4; ++m) {
;                 const int row = row0 + ai * 128 + m * 16; const size_t off = (size_t)row * DM + col0; float q = 0.f;
; #pragma unroll
;                 for (int bj = 0; bj < 2; ++bj)
; #pragma unroll
;                     for (int n = 0; n < 2; ++n) { const size_t o = off + bj * 128 + n * 16; const f32x4 xv = *(const f32x4*)(xin + o) + acc[ai][bj][m][n]; *(f32x4*)(xout + o) = xv;
;                         q += (xv[0] * xv[0] + xv[1] * xv[1]) + (xv[2] * xv[2] + xv[3] * xv[3]);
;                         u32x2 w; w.x = cvt_pk_bf16(xv[0], xv[1]); w.y = cvt_pk_bf16(xv[2], xv[3]); *(u32x2*)(xb + o) = w; }
;                 q += __shfl_xor(q, 16); q += __shfl_xor(q, 32);
;                 if (fq == 0) ssq[(size_t)row * 16 + u.pn * 4 + wc] = q;
;             }
	v_add_f32_e32 v179, v179, v177
	ds_bpermute_b32 v178, v172, v179
	s_waitcnt lgkmcnt(0)
	v_add_f32_e32 v179, v179, v178
	s_and_saveexec_b64 s[62:63], s[4:5]
	global_store_dword v176, v179, s[14:15]
	s_mov_b64 exec, s[62:63]
	v_add_u32_e32 v173, 0x80000, v138
	global_load_dwordx4 v[214:217], v173, s[18:19]
	global_load_dwordx4 v[218:221], v173, s[18:19] offset:64
	global_load_dwordx4 v[222:225], v173, s[18:19] offset:512
	global_load_dwordx4 v[226:229], v173, s[18:19] offset:576
	v_add_u32_e32 v174, 0x20000, v138
	v_add_u32_e32 v175, 0x10000, v139
	v_add_u32_e32 v176, 0x800, v140
	s_waitcnt vmcnt(29)
	v_pk_add_f32 v[158:159], v[96:97], v[158:159]
	v_pk_add_f32 v[156:157], v[94:95], v[156:157]
	global_store_dwordx4 v174, v[156:159], s[12:13]
	v_mul_f32_e32 v178, v159, v159
	v_mul_f32_e32 v177, v157, v157
	v_fmac_f32_e32 v177, v156, v156
	v_fmac_f32_e32 v178, v158, v158
	v_cvt_pk_bf16_f32 v180, v156, v157
	v_cvt_pk_bf16_f32 v181, v158, v159
	v_add_f32_e32 v179, v177, v178
	global_store_dwordx2 v175, v[180:181], s[48:49]
	s_waitcnt vmcnt(30)
	v_pk_add_f32 v[162:163], v[92:93], v[162:163]
	v_pk_add_f32 v[160:161], v[90:91], v[160:161]
	global_store_dwordx4 v174, v[160:163], s[12:13] offset:64
	v_mul_f32_e32 v178, v163, v163
	v_mul_f32_e32 v177, v161, v161
	v_fmac_f32_e32 v177, v160, v160
	v_fmac_f32_e32 v178, v162, v162
	v_cvt_pk_bf16_f32 v182, v160, v161
	v_cvt_pk_bf16_f32 v183, v162, v163
	v_add_f32_e32 v177, v177, v178
	v_add_f32_e32 v179, v179, v177
	global_store_dwordx2 v175, v[182:183], s[48:49] offset:32
	s_waitcnt vmcnt(31)
	v_pk_add_f32 v[166:167], v[88:89], v[166:167]
	v_pk_add_f32 v[164:165], v[86:87], v[164:165]
	global_store_dwordx4 v174, v[164:167], s[12:13] offset:512
	v_mul_f32_e32 v178, v167, v167
	v_mul_f32_e32 v177, v165, v165
	v_fmac_f32_e32 v177, v164, v164
	v_fmac_f32_e32 v178, v166, v166
	v_cvt_pk_bf16_f32 v180, v164, v165
	v_cvt_pk_bf16_f32 v181, v166, v167
	v_add_f32_e32 v177, v177, v178
	v_add_f32_e32 v179, v179, v177
	global_store_dwordx2 v175, v[180:181], s[48:49] offset:256
	s_waitcnt vmcnt(32)
	v_pk_add_f32 v[170:171], v[84:85], v[170:171]
	v_pk_add_f32 v[168:169], v[82:83], v[168:169]
	global_store_dwordx4 v174, v[168:171], s[12:13] offset:576
	v_mul_f32_e32 v178, v171, v171
	v_mul_f32_e32 v177, v169, v169
	v_fmac_f32_e32 v177, v168, v168
	v_fmac_f32_e32 v178, v170, v170
	v_cvt_pk_bf16_f32 v182, v168, v169
	v_cvt_pk_bf16_f32 v183, v170, v171
	v_add_f32_e32 v177, v177, v178
	v_add_f32_e32 v179, v179, v177
	global_store_dwordx2 v175, v[182:183], s[48:49] offset:288
	ds_bpermute_b32 v177, v141, v179
	s_waitcnt lgkmcnt(0)
	v_add_f32_e32 v179, v179, v177
	ds_bpermute_b32 v178, v172, v179
	s_waitcnt lgkmcnt(0)
	v_add_f32_e32 v179, v179, v178
	s_and_saveexec_b64 s[62:63], s[4:5]
	global_store_dword v176, v179, s[14:15]
	s_mov_b64 exec, s[62:63]
	v_add_u32_e32 v173, 0x90000, v138
	global_load_dwordx4 v[156:159], v173, s[18:19]
	global_load_dwordx4 v[160:163], v173, s[18:19] offset:64
	global_load_dwordx4 v[164:167], v173, s[18:19] offset:512
	global_load_dwordx4 v[168:171], v173, s[18:19] offset:576
	v_add_u32_e32 v174, 0x30000, v138
	v_add_u32_e32 v175, 0x18000, v139
	v_add_u32_e32 v176, 0xc00, v140
	s_waitcnt vmcnt(29)
	v_pk_add_f32 v[200:201], v[80:81], v[200:201]
	v_pk_add_f32 v[198:199], v[78:79], v[198:199]
	global_store_dwordx4 v174, v[198:201], s[12:13]
	v_mul_f32_e32 v178, v201, v201
	v_mul_f32_e32 v177, v199, v199
	v_fmac_f32_e32 v177, v198, v198
	v_fmac_f32_e32 v178, v200, v200
	v_cvt_pk_bf16_f32 v180, v198, v199
	v_cvt_pk_bf16_f32 v181, v200, v201
	v_add_f32_e32 v179, v177, v178
	global_store_dwordx2 v175, v[180:181], s[48:49]
	s_waitcnt vmcnt(30)
	v_pk_add_f32 v[204:205], v[76:77], v[204:205]
	v_pk_add_f32 v[202:203], v[74:75], v[202:203]
	global_store_dwordx4 v174, v[202:205], s[12:13] offset:64
	v_mul_f32_e32 v178, v205, v205
	v_mul_f32_e32 v177, v203, v203
	v_fmac_f32_e32 v177, v202, v202
	v_fmac_f32_e32 v178, v204, v204
	v_cvt_pk_bf16_f32 v182, v202, v203
	v_cvt_pk_bf16_f32 v183, v204, v205
	v_add_f32_e32 v177, v177, v178
	v_add_f32_e32 v179, v179, v177
	global_store_dwordx2 v175, v[182:183], s[48:49] offset:32
	s_waitcnt vmcnt(31)
	v_pk_add_f32 v[208:209], v[72:73], v[208:209]
	v_pk_add_f32 v[206:207], v[70:71], v[206:207]
	global_store_dwordx4 v174, v[206:209], s[12:13] offset:512
	v_mul_f32_e32 v178, v209, v209
	v_mul_f32_e32 v177, v207, v207
	v_fmac_f32_e32 v177, v206, v206
	v_fmac_f32_e32 v178, v208, v208
	v_cvt_pk_bf16_f32 v180, v206, v207
	v_cvt_pk_bf16_f32 v181, v208, v209
	v_add_f32_e32 v177, v177, v178
	v_add_f32_e32 v179, v179, v177
	global_store_dwordx2 v175, v[180:181], s[48:49] offset:256
	s_waitcnt vmcnt(32)
	v_pk_add_f32 v[212:213], v[68:69], v[212:213]
	v_pk_add_f32 v[210:211], v[66:67], v[210:211]
	global_store_dwordx4 v174, v[210:213], s[12:13] offset:576
	v_mul_f32_e32 v178, v213, v213
	v_mul_f32_e32 v177, v211, v211
	v_fmac_f32_e32 v177, v210, v210
	v_fmac_f32_e32 v178, v212, v212
	v_cvt_pk_bf16_f32 v182, v210, v211
	v_cvt_pk_bf16_f32 v183, v212, v213
	v_add_f32_e32 v177, v177, v178
	v_add_f32_e32 v179, v179, v177
	global_store_dwordx2 v175, v[182:183], s[48:49] offset:288
	ds_bpermute_b32 v177, v141, v179
	s_waitcnt lgkmcnt(0)
	v_add_f32_e32 v179, v179, v177
	ds_bpermute_b32 v178, v172, v179
	s_waitcnt lgkmcnt(0)
	v_add_f32_e32 v179, v179, v178
	s_and_saveexec_b64 s[62:63], s[4:5]
	global_store_dword v176, v179, s[14:15]
	s_mov_b64 exec, s[62:63]
	v_add_u32_e32 v173, 0xa0000, v138
	global_load_dwordx4 v[198:201], v173, s[18:19]
	global_load_dwordx4 v[202:205], v173, s[18:19] offset:64
	global_load_dwordx4 v[206:209], v173, s[18:19] offset:512
	global_load_dwordx4 v[210:213], v173, s[18:19] offset:576
	v_add_u32_e32 v174, 0x80000, v138
	v_add_u32_e32 v175, 0x40000, v139
	v_add_u32_e32 v176, 0x2000, v140
	s_waitcnt vmcnt(29)
; #define LAS __attribute__((address_space(3)))
; __device__ __forceinline__ unsigned cvt_pk_bf16(float lo, float hi) { unsigned r; asm volatile("v_cvt_pk_bf16_f32 %0, %1, %2" : "=v"(r) : "v"(lo), "v"(hi)); return r; }
;     __device__ __forceinline__ void operator()(const f32x4 (&acc)[2][2][4][2], const pg8::Unit& u, int wr, int wc, int fr, int fq, LAS unsigned char*) const {
;         const int row0 = u.pm * 256 + wr * 64 + fr, col0 = u.pn * 256 + wc * 32 + 4 * fq;
; #pragma unroll
;         for (int ai = 0; ai < 2; ++ai)
; #pragma unroll
;             for (int m = 0; m < 4; ++m) {
;                 const int row = row0 + ai * 128 + m * 16; const size_t off = (size_t)row * DM + col0; float q = 0.f;
; #pragma unroll
;                 for (int bj = 0; bj < 2; ++bj)
; #pragma unroll
;                     for (int n = 0; n < 2; ++n) { const size_t o = off + bj * 128 + n * 16; const f32x4 xv = *(const f32x4*)(xin + o) + acc[ai][bj][m][n]; *(f32x4*)(xout + o) = xv;
;                         q += (xv[0] * xv[0] + xv[1] * xv[1]) + (xv[2] * xv[2] + xv[3] * xv[3]);
;                         u32x2 w; w.x = cvt_pk_bf16(xv[0], xv[1]); w.y = cvt_pk_bf16(xv[2], xv[3]); *(u32x2*)(xb + o) = w; }
;                 q += __shfl_xor(q, 16); q += __shfl_xor(q, 32);
;                 if (fq == 0) ssq[(size_t)row * 16 + u.pn * 4 + wc] = q;
;             }
	v_pk_add_f32 v[216:217], v[64:65], v[216:217]
	v_pk_add_f32 v[214:215], v[62:63], v[214:215]
	global_store_dwordx4 v174, v[214:217], s[12:13]
	v_mul_f32_e32 v178, v217, v217
	v_mul_f32_e32 v177, v215, v215
	v_fmac_f32_e32 v177, v214, v214
	v_fmac_f32_e32 v178, v216, v216
	v_cvt_pk_bf16_f32 v180, v214, v215
	v_cvt_pk_bf16_f32 v181, v216, v217
	v_add_f32_e32 v179, v177, v178
	global_store_dwordx2 v175, v[180:181], s[48:49]
	s_waitcnt vmcnt(30)
	v_pk_add_f32 v[220:221], v[60:61], v[220:221]
	v_pk_add_f32 v[218:219], v[58:59], v[218:219]
	global_store_dwordx4 v174, v[218:221], s[12:13] offset:64
	v_mul_f32_e32 v178, v221, v221
	v_mul_f32_e32 v177, v219, v219
	v_fmac_f32_e32 v177, v218, v218
	v_fmac_f32_e32 v178, v220, v220
	v_cvt_pk_bf16_f32 v182, v218, v219
	v_cvt_pk_bf16_f32 v183, v220, v221
	v_add_f32_e32 v177, v177, v178
	v_add_f32_e32 v179, v179, v177
	global_store_dwordx2 v175, v[182:183], s[48:49] offset:32
	s_waitcnt vmcnt(31)
	v_pk_add_f32 v[224:225], v[56:57], v[224:225]
	v_pk_add_f32 v[222:223], v[54:55], v[222:223]
	global_store_dwordx4 v174, v[222:225], s[12:13] offset:512
	v_mul_f32_e32 v178, v225, v225
	v_mul_f32_e32 v177, v223, v223
	v_fmac_f32_e32 v177, v222, v222
	v_fmac_f32_e32 v178, v224, v224
	v_cvt_pk_bf16_f32 v180, v222, v223
	v_cvt_pk_bf16_f32 v181, v224, v225
	v_add_f32_e32 v177, v177, v178
	v_add_f32_e32 v179, v179, v177
	global_store_dwordx2 v175, v[180:181], s[48:49] offset:256
	s_waitcnt vmcnt(32)
	v_pk_add_f32 v[228:229], v[52:53], v[228:229]
	v_pk_add_f32 v[226:227], v[50:51], v[226:227]
	global_store_dwordx4 v174, v[226:229], s[12:13] offset:576
	v_mul_f32_e32 v178, v229, v229
	v_mul_f32_e32 v177, v227, v227
	v_fmac_f32_e32 v177, v226, v226
	v_fmac_f32_e32 v178, v228, v228
	v_cvt_pk_bf16_f32 v182, v226, v227
	v_cvt_pk_bf16_f32 v183, v228, v229
	v_add_f32_e32 v177, v177, v178
	v_add_f32_e32 v179, v179, v177
	global_store_dwordx2 v175, v[182:183], s[48:49] offset:288
	ds_bpermute_b32 v177, v141, v179
	s_waitcnt lgkmcnt(0)
	v_add_f32_e32 v179, v179, v177
	ds_bpermute_b32 v178, v172, v179
	s_waitcnt lgkmcnt(0)
	v_add_f32_e32 v179, v179, v178
	s_and_saveexec_b64 s[62:63], s[4:5]
	global_store_dword v176, v179, s[14:15]
	s_mov_b64 exec, s[62:63]
	v_add_u32_e32 v173, 0xb0000, v138
	global_load_dwordx4 v[214:217], v173, s[18:19]
	global_load_dwordx4 v[218:221], v173, s[18:19] offset:64
	global_load_dwordx4 v[222:225], v173, s[18:19] offset:512
	global_load_dwordx4 v[226:229], v173, s[18:19] offset:576
	v_add_u32_e32 v174, 0x90000, v138
	v_add_u32_e32 v175, 0x48000, v139
	v_add_u32_e32 v176, 0x2400, v140
	s_waitcnt vmcnt(29)
	v_pk_add_f32 v[158:159], v[48:49], v[158:159]
	v_pk_add_f32 v[156:157], v[46:47], v[156:157]
	global_store_dwordx4 v174, v[156:159], s[12:13]
	v_mul_f32_e32 v178, v159, v159
	v_mul_f32_e32 v177, v157, v157
	v_fmac_f32_e32 v177, v156, v156
	v_fmac_f32_e32 v178, v158, v158
	v_cvt_pk_bf16_f32 v180, v156, v157
	v_cvt_pk_bf16_f32 v181, v158, v159
	v_add_f32_e32 v179, v177, v178
	global_store_dwordx2 v175, v[180:181], s[48:49]
	s_waitcnt vmcnt(30)
	v_pk_add_f32 v[162:163], v[44:45], v[162:163]
	v_pk_add_f32 v[160:161], v[42:43], v[160:161]
	global_store_dwordx4 v174, v[160:163], s[12:13] offset:64
	v_mul_f32_e32 v178, v163, v163
	v_mul_f32_e32 v177, v161, v161
	v_fmac_f32_e32 v177, v160, v160
	v_fmac_f32_e32 v178, v162, v162
	v_cvt_pk_bf16_f32 v182, v160, v161
	v_cvt_pk_bf16_f32 v183, v162, v163
	v_add_f32_e32 v177, v177, v178
	v_add_f32_e32 v179, v179, v177
	global_store_dwordx2 v175, v[182:183], s[48:49] offset:32
	s_waitcnt vmcnt(31)
	v_pk_add_f32 v[166:167], v[40:41], v[166:167]
	v_pk_add_f32 v[164:165], v[38:39], v[164:165]
	global_store_dwordx4 v174, v[164:167], s[12:13] offset:512
	v_mul_f32_e32 v178, v167, v167
	v_mul_f32_e32 v177, v165, v165
	v_fmac_f32_e32 v177, v164, v164
	v_fmac_f32_e32 v178, v166, v166
	v_cvt_pk_bf16_f32 v180, v164, v165
	v_cvt_pk_bf16_f32 v181, v166, v167
	v_add_f32_e32 v177, v177, v178
	v_add_f32_e32 v179, v179, v177
	global_store_dwordx2 v175, v[180:181], s[48:49] offset:256
	s_waitcnt vmcnt(32)
	v_pk_add_f32 v[170:171], v[36:37], v[170:171]
	v_pk_add_f32 v[168:169], v[34:35], v[168:169]
	global_store_dwordx4 v174, v[168:171], s[12:13] offset:576
	v_mul_f32_e32 v178, v171, v171
	v_mul_f32_e32 v177, v169, v169
	v_fmac_f32_e32 v177, v168, v168
	v_fmac_f32_e32 v178, v170, v170
	v_cvt_pk_bf16_f32 v182, v168, v169
	v_cvt_pk_bf16_f32 v183, v170, v171
	v_add_f32_e32 v177, v177, v178
	v_add_f32_e32 v179, v179, v177
	global_store_dwordx2 v175, v[182:183], s[48:49] offset:288
	ds_bpermute_b32 v177, v141, v179
	s_waitcnt lgkmcnt(0)
	v_add_f32_e32 v179, v179, v177
	ds_bpermute_b32 v178, v172, v179
	s_waitcnt lgkmcnt(0)
	v_add_f32_e32 v179, v179, v178
	s_and_saveexec_b64 s[62:63], s[4:5]
	global_store_dword v176, v179, s[14:15]
	s_mov_b64 exec, s[62:63]
	v_add_u32_e32 v174, 0xa0000, v138
	v_add_u32_e32 v175, 0x50000, v139
	v_add_u32_e32 v176, 0x2800, v140
	s_waitcnt vmcnt(25)
; #define LAS __attribute__((address_space(3)))
; __device__ __forceinline__ unsigned cvt_pk_bf16(float lo, float hi) { unsigned r; asm volatile("v_cvt_pk_bf16_f32 %0, %1, %2" : "=v"(r) : "v"(lo), "v"(hi)); return r; }
;     __device__ __forceinline__ void operator()(const f32x4 (&acc)[2][2][4][2], const pg8::Unit& u, int wr, int wc, int fr, int fq, LAS unsigned char*) const {
;         const int row0 = u.pm * 256 + wr * 64 + fr, col0 = u.pn * 256 + wc * 32 + 4 * fq;
; #pragma unroll
;         for (int ai = 0; ai < 2; ++ai)
; #pragma unroll
;             for (int m = 0; m < 4; ++m) {
;                 const int row = row0 + ai * 128 + m * 16; const size_t off = (size_t)row * DM + col0; float q = 0.f;
; #pragma unroll
;                 for (int bj = 0; bj < 2; ++bj)
; #pragma unroll
;                     for (int n = 0; n < 2; ++n) { const size_t o = off + bj * 128 + n * 16; const f32x4 xv = *(const f32x4*)(xin + o) + acc[ai][bj][m][n]; *(f32x4*)(xout + o) = xv;
;                         q += (xv[0] * xv[0] + xv[1] * xv[1]) + (xv[2] * xv[2] + xv[3] * xv[3]);
;                         u32x2 w; w.x = cvt_pk_bf16(xv[0], xv[1]); w.y = cvt_pk_bf16(xv[2], xv[3]); *(u32x2*)(xb + o) = w; }
;                 q += __shfl_xor(q, 16); q += __shfl_xor(q, 32);
;                 if (fq == 0) ssq[(size_t)row * 16 + u.pn * 4 + wc] = q;
;             }
	v_pk_add_f32 v[200:201], v[32:33], v[200:201]
	v_pk_add_f32 v[198:199], v[30:31], v[198:199]
	global_store_dwordx4 v174, v[198:201], s[12:13]
	v_mul_f32_e32 v178, v201, v201
	v_mul_f32_e32 v177, v199, v199
	v_fmac_f32_e32 v177, v198, v198
	v_fmac_f32_e32 v178, v200, v200
	v_cvt_pk_bf16_f32 v180, v198, v199
	v_cvt_pk_bf16_f32 v181, v200, v201
	v_add_f32_e32 v179, v177, v178
	global_store_dwordx2 v175, v[180:181], s[48:49]
	s_waitcnt vmcnt(26)
	v_pk_add_f32 v[204:205], v[28:29], v[204:205]
	v_pk_add_f32 v[202:203], v[26:27], v[202:203]
	global_store_dwordx4 v174, v[202:205], s[12:13] offset:64
	v_mul_f32_e32 v178, v205, v205
	v_mul_f32_e32 v177, v203, v203
	v_fmac_f32_e32 v177, v202, v202
	v_fmac_f32_e32 v178, v204, v204
	v_cvt_pk_bf16_f32 v182, v202, v203
	v_cvt_pk_bf16_f32 v183, v204, v205
	v_add_f32_e32 v177, v177, v178
	v_add_f32_e32 v179, v179, v177
	global_store_dwordx2 v175, v[182:183], s[48:49] offset:32
	s_waitcnt vmcnt(27)
	v_pk_add_f32 v[208:209], v[24:25], v[208:209]
	v_pk_add_f32 v[206:207], v[22:23], v[206:207]
	global_store_dwordx4 v174, v[206:209], s[12:13] offset:512
	v_mul_f32_e32 v178, v209, v209
	v_mul_f32_e32 v177, v207, v207
	v_fmac_f32_e32 v177, v206, v206
	v_fmac_f32_e32 v178, v208, v208
	v_cvt_pk_bf16_f32 v180, v206, v207
	v_cvt_pk_bf16_f32 v181, v208, v209
	v_add_f32_e32 v177, v177, v178
	v_add_f32_e32 v179, v179, v177
	global_store_dwordx2 v175, v[180:181], s[48:49] offset:256
	s_waitcnt vmcnt(28)
	v_pk_add_f32 v[212:213], v[20:21], v[212:213]
	v_pk_add_f32 v[210:211], v[18:19], v[210:211]
	global_store_dwordx4 v174, v[210:213], s[12:13] offset:576
	v_mul_f32_e32 v178, v213, v213
	v_mul_f32_e32 v177, v211, v211
	v_fmac_f32_e32 v177, v210, v210
	v_fmac_f32_e32 v178, v212, v212
	v_cvt_pk_bf16_f32 v182, v210, v211
	v_cvt_pk_bf16_f32 v183, v212, v213
	v_add_f32_e32 v177, v177, v178
	v_add_f32_e32 v179, v179, v177
	global_store_dwordx2 v175, v[182:183], s[48:49] offset:288
	ds_bpermute_b32 v177, v141, v179
	s_waitcnt lgkmcnt(0)
	v_add_f32_e32 v179, v179, v177
	ds_bpermute_b32 v178, v172, v179
	s_waitcnt lgkmcnt(0)
	v_add_f32_e32 v179, v179, v178
	s_and_saveexec_b64 s[62:63], s[4:5]
	global_store_dword v176, v179, s[14:15]
	s_mov_b64 exec, s[62:63]
	v_add_u32_e32 v174, 0xb0000, v138
	v_add_u32_e32 v175, 0x58000, v139
	v_add_u32_e32 v176, 0x2c00, v140
	s_waitcnt vmcnt(21)
	v_pk_add_f32 v[216:217], v[16:17], v[216:217]
	v_pk_add_f32 v[214:215], v[14:15], v[214:215]
	global_store_dwordx4 v174, v[214:217], s[12:13]
	v_mul_f32_e32 v178, v217, v217
	v_mul_f32_e32 v177, v215, v215
	v_fmac_f32_e32 v177, v214, v214
	v_fmac_f32_e32 v178, v216, v216
	v_cvt_pk_bf16_f32 v180, v214, v215
	v_cvt_pk_bf16_f32 v181, v216, v217
	v_add_f32_e32 v179, v177, v178
	global_store_dwordx2 v175, v[180:181], s[48:49]
	s_waitcnt vmcnt(22)
	v_pk_add_f32 v[220:221], v[12:13], v[220:221]
	v_pk_add_f32 v[218:219], v[10:11], v[218:219]
	global_store_dwordx4 v174, v[218:221], s[12:13] offset:64
	v_mul_f32_e32 v178, v221, v221
	v_mul_f32_e32 v177, v219, v219
	v_fmac_f32_e32 v177, v218, v218
	v_fmac_f32_e32 v178, v220, v220
	v_cvt_pk_bf16_f32 v182, v218, v219
	v_cvt_pk_bf16_f32 v183, v220, v221
	v_add_f32_e32 v177, v177, v178
	v_add_f32_e32 v179, v179, v177
	global_store_dwordx2 v175, v[182:183], s[48:49] offset:32
	s_waitcnt vmcnt(23)
	v_pk_add_f32 v[224:225], v[8:9], v[224:225]
	v_pk_add_f32 v[222:223], v[6:7], v[222:223]
	global_store_dwordx4 v174, v[222:225], s[12:13] offset:512
	v_mul_f32_e32 v178, v225, v225
	v_mul_f32_e32 v177, v223, v223
	v_fmac_f32_e32 v177, v222, v222
	v_fmac_f32_e32 v178, v224, v224
	v_cvt_pk_bf16_f32 v180, v222, v223
	v_cvt_pk_bf16_f32 v181, v224, v225
	v_add_f32_e32 v177, v177, v178
	v_add_f32_e32 v179, v179, v177
	global_store_dwordx2 v175, v[180:181], s[48:49] offset:256
	s_waitcnt vmcnt(24)
	v_pk_add_f32 v[228:229], v[4:5], v[228:229]
	v_pk_add_f32 v[226:227], v[2:3], v[226:227]
	global_store_dwordx4 v174, v[226:229], s[12:13] offset:576
	v_mul_f32_e32 v178, v229, v229
	v_mul_f32_e32 v177, v227, v227
	v_fmac_f32_e32 v177, v226, v226
	v_fmac_f32_e32 v178, v228, v228
	v_cvt_pk_bf16_f32 v182, v226, v227
	v_cvt_pk_bf16_f32 v183, v228, v229
	v_add_f32_e32 v177, v177, v178
	v_add_f32_e32 v179, v179, v177
	global_store_dwordx2 v175, v[182:183], s[48:49] offset:288
	ds_bpermute_b32 v177, v141, v179
	s_waitcnt lgkmcnt(0)
	v_add_f32_e32 v179, v179, v177
	ds_bpermute_b32 v178, v172, v179
	s_waitcnt lgkmcnt(0)
	v_add_f32_e32 v179, v179, v178
	s_and_saveexec_b64 s[62:63], s[4:5]
	global_store_dword v176, v179, s[14:15]
	s_mov_b64 exec, s[62:63]
	s_andn2_b64 vcc, exec, s[6:7]
	s_mov_b64 s[6:7], -1
	s_cbranch_vccnz .LBB0_53
	s_andn2_b64 vcc, exec, s[22:23]
	s_cbranch_vccnz .LBB0_52
	s_barrier
	s_branch .LBB0_52

; #define LAS __attribute__((address_space(3)))
; __device__ __forceinline__ float bflo(unsigned w) { return __uint_as_float(w << 16); }
; __device__ __forceinline__ float bfhi(unsigned w) { return __uint_as_float(w & 0xffff0000u); }
; __device__ __forceinline__ void retout_unit(CArgs& a, int l, unsigned char* lds, int u, const int tid) {
;     ...
;     const float lg2 = log2f(1.f - exp2f(-5.f - (float)h));
;     const size_t row0 = (size_t)b * SEQ + n * 128;
;     LAS bf16_t* KS = (LAS bf16_t*)lds; LAS bf16_t* VT = KS + 128 * RP64; LAS bf16_t* RT = VT + 64 * RP128; LAS bf16_t* PS = RT + 64 * RP64;
;     __syncthreads();
;     { const int r = tid >> 2, c0 = (tid & 3) * 16;
;       const u32x4* ksrc = (const u32x4*)(RK + (row0 + r) * 256 + h * 64 + c0); const u32x4 k0 = ksrc[0], k1 = ksrc[1];
;       *(LAS u32x4*)(KS + r * RP64 + c0) = k0; *(LAS u32x4*)(KS + r * RP64 + c0 + 8) = k1;
;       const u32x4* vs = (const u32x4*)(RV + (row0 + r) * 256 + h * 64 + c0); const u32x4 a0 = vs[0], a1 = vs[1];
;       const unsigned vw[8] = {a0.x, a0.y, a0.z, a0.w, a1.x, a1.y, a1.z, a1.w};
; #pragma unroll
;       for (int i = 0; i < 8; ++i) { VT[(c0 + 2 * i) * RP128 + r] = (bf16_t)(vw[i] & 0xffffu); VT[(c0 + 2 * i + 1) * RP128 + r] = (bf16_t)(vw[i] >> 16); } }
;     { float r[8];
; #pragma unroll
;       for (int i = 0; i < 8; ++i) r[i] = 0.f;
; #pragma unroll 8
;       for (int m = 0; m < n; ++m) { const float wgt = exp2f(lg2 * 128.f * (float)(n - 1 - m)); const u32x4 v = *(const u32x4*)(KV + (size_t)(u - n + m) * 4096 + tid * 8);
;           r[0] += wgt * bflo(v.x); r[1] += wgt * bfhi(v.x); r[2] += wgt * bflo(v.y); r[3] += wgt * bfhi(v.y); r[4] += wgt * bflo(v.z); r[5] += wgt * bfhi(v.z); r[6] += wgt * bflo(v.w); r[7] += wgt * bfhi(v.w); }
.LBB0_126:
	s_bfe_u32 s44, s42, 0x20005
	v_cvt_f32_ubyte0_e32 v0, s44
	v_sub_f32_e32 v0, 0xc0a00000, v0
	v_cmp_gt_f32_e32 vcc, s87, v0
	s_lshr_b32 s63, s42, 5
	s_and_b32 s65, s63, 24
	v_cndmask_b32_e32 v2, 0, v189, vcc
	v_add_f32_e32 v0, v0, v2
	s_add_i32 s6, s65, s42
	v_exp_f32_e32 v0, v0
	s_and_b32 s45, s6, 31
	s_ashr_i32 s58, s42, 7
	s_and_b64 s[6:7], vcc, exec
	s_cselect_b32 s6, 0xffffffc0, 0
	s_ashr_i32 s59, s58, 31
	v_ldexp_f32 v0, v0, s6
	s_lshl_b64 s[56:57], s[58:59], 12
	s_lshl_b32 s6, s45, 7
	s_or_b32 s6, s56, s6
	s_mov_b32 s7, s57
	v_lshl_add_u64 v[4:5], s[6:7], 0, v[68:69]
	v_lshlrev_b64 v[12:13], 9, v[4:5]
	v_lshl_add_u64 v[4:5], s[14:15], 0, v[12:13]
	s_lshl_b32 s28, s44, 7
	v_lshl_add_u64 v[4:5], v[4:5], 0, s[28:29]
	v_mov_b32_e32 v91, v1
	v_lshl_add_u64 v[8:9], v[4:5], 0, v[90:91]
	s_waitcnt vmcnt(0)
	s_barrier
	global_load_dwordx4 v[4:7], v[8:9], off offset:16
	s_nop 0
	global_load_dwordx4 v[8:11], v[8:9], off
	v_sub_f32_e32 v0, 1.0, v0
	v_cmp_gt_f32_e32 vcc, s74, v0
	s_and_b64 s[26:27], vcc, exec
	s_cselect_b32 s26, 32, 0
	v_ldexp_f32 v0, v0, s26
	v_log_f32_e32 v0, v0
	s_cmp_eq_u32 s45, 0
	v_cndmask_b32_e32 v2, 0, v190, vcc
	s_cselect_b64 s[60:61], -1, 0
	v_mov_b32_e32 v3, 0
	v_readfirstlane_b32 s43, v66
	s_and_b64 vcc, exec, s[60:61]
	s_waitcnt vmcnt(0)
	ds_write_b128 v96, v[8:11]
	ds_write_b128 v96, v[4:7] offset:16
	v_lshl_add_u64 v[4:5], s[48:49], 0, v[12:13]
	v_lshl_add_u64 v[4:5], v[4:5], 0, s[28:29]
	v_lshl_add_u64 v[8:9], v[4:5], 0, v[90:91]
	global_load_dwordx4 v[4:7], v[8:9], off
	v_sub_f32_e32 v91, v0, v2
	v_mov_b32_e32 v2, 0
	s_waitcnt vmcnt(0)
	ds_write_b16 v97, v4 offset:18432
	ds_write_b16_d16_hi v97, v4 offset:18704
	ds_write_b16 v97, v5 offset:18976
	ds_write_b16_d16_hi v97, v5 offset:19248
	ds_write_b16 v97, v6 offset:19520
	ds_write_b16_d16_hi v97, v6 offset:19792
	ds_write_b16 v97, v7 offset:20064
	ds_write_b16_d16_hi v97, v7 offset:20336
	global_load_dwordx4 v[4:7], v[8:9], off offset:16
	v_mov_b32_e32 v9, 0
	v_mov_b32_e32 v8, 0
	s_waitcnt vmcnt(0)
	ds_write_b16 v97, v4 offset:20608
	ds_write_b16_d16_hi v97, v4 offset:20880
	ds_write_b16 v97, v5 offset:21152
	ds_write_b16_d16_hi v97, v5 offset:21424
	ds_write_b16 v97, v6 offset:21696
	ds_write_b16_d16_hi v97, v6 offset:21968
	ds_write_b16 v97, v7 offset:22240
	ds_write_b16_d16_hi v97, v7 offset:22512
	v_mov_b32_e32 v5, 0
	v_mov_b32_e32 v4, 0
	v_mov_b32_e32 v7, 0
	v_mov_b32_e32 v6, 0
	s_cbranch_vccnz .LBB0_134
	s_mul_i32 s26, s19, s10
	s_add_i32 s26, s26, s11
	s_add_i32 s26, s26, s65
	s_and_b32 s64, s26, 31
	s_lshl_b32 s62, s63, 5
	v_mul_f32_e32 v12, 0x43000000, v91
	s_ashr_i32 s63, s62, 31
	s_lshl_b64 s[26:27], s[62:63], 13
	v_lshl_add_u64 v[10:11], v[70:71], 0, s[26:27]
	s_mov_b32 s65, 0
	s_add_i32 s59, s64, -1
	s_mov_b32 s63, 0
.Lrt_batch:
	s_add_i32 s62, s65, 0
	s_min_i32 s62, s62, s59
	s_lshl_b32 s62, s62, 13
	v_lshl_add_u64 v[240:241], v[10:11], 0, s[62:63]
	global_load_dwordx4 v[208:211], v[240:241], off
	s_add_i32 s62, s65, 1
	s_min_i32 s62, s62, s59
	s_lshl_b32 s62, s62, 13
	v_lshl_add_u64 v[240:241], v[10:11], 0, s[62:63]
	global_load_dwordx4 v[212:215], v[240:241], off
	s_add_i32 s62, s65, 2
	s_min_i32 s62, s62, s59
	s_lshl_b32 s62, s62, 13
	v_lshl_add_u64 v[240:241], v[10:11], 0, s[62:63]
	global_load_dwordx4 v[216:219], v[240:241], off
	s_add_i32 s62, s65, 3
	s_min_i32 s62, s62, s59
	s_lshl_b32 s62, s62, 13
	v_lshl_add_u64 v[240:241], v[10:11], 0, s[62:63]
	global_load_dwordx4 v[220:223], v[240:241], off
	s_add_i32 s62, s65, 4
	s_min_i32 s62, s62, s59
	s_lshl_b32 s62, s62, 13
	v_lshl_add_u64 v[240:241], v[10:11], 0, s[62:63]
	global_load_dwordx4 v[224:227], v[240:241], off
	s_add_i32 s62, s65, 5
	s_min_i32 s62, s62, s59
	s_lshl_b32 s62, s62, 13
	v_lshl_add_u64 v[240:241], v[10:11], 0, s[62:63]
	global_load_dwordx4 v[228:231], v[240:241], off
	s_add_i32 s62, s65, 6
	s_min_i32 s62, s62, s59
	s_lshl_b32 s62, s62, 13
	v_lshl_add_u64 v[240:241], v[10:11], 0, s[62:63]
	global_load_dwordx4 v[232:235], v[240:241], off
	s_add_i32 s62, s65, 7
	s_min_i32 s62, s62, s59
	s_lshl_b32 s62, s62, 13
	v_lshl_add_u64 v[240:241], v[10:11], 0, s[62:63]
	global_load_dwordx4 v[236:239], v[240:241], off
	s_add_i32 s45, s65, 0
	s_sub_i32 s28, s59, s45
	s_cmp_lt_i32 s45, s64
	s_cselect_b32 s30, -1, 0
	v_cvt_f32_i32_e32 v0, s28
	v_mul_f32_e32 v13, v12, v0
	v_cmp_gt_f32_e32 vcc, s87, v13
	s_and_b64 s[26:27], vcc, exec
	s_cselect_b32 s26, 0xffffffc0, 0
	v_cndmask_b32_e32 v13, 0, v189, vcc
	v_fmac_f32_e32 v13, v12, v0
	v_exp_f32_e32 v0, v13
	s_waitcnt vmcnt(7)
	v_ldexp_f32 v0, v0, s26
	v_and_b32_e32 v0, s30, v0
	v_lshlrev_b32_e32 v14, 16, v208
	v_and_b32_e32 v15, 0xffff0000, v208
	v_pk_fma_f32 v[8:9], v[0:1], v[14:15], v[8:9] op_sel_hi:[0,1,1]
	v_lshlrev_b32_e32 v16, 16, v209
	v_and_b32_e32 v17, 0xffff0000, v209
	v_pk_fma_f32 v[6:7], v[0:1], v[16:17], v[6:7] op_sel_hi:[0,1,1]
	v_lshlrev_b32_e32 v18, 16, v210
	v_and_b32_e32 v19, 0xffff0000, v210
	v_pk_fma_f32 v[4:5], v[0:1], v[18:19], v[4:5] op_sel_hi:[0,1,1]
	v_lshlrev_b32_e32 v14, 16, v211
	v_and_b32_e32 v15, 0xffff0000, v211
	v_pk_fma_f32 v[2:3], v[0:1], v[14:15], v[2:3] op_sel_hi:[0,1,1]
	s_add_i32 s45, s65, 1
	s_sub_i32 s28, s59, s45
	s_cmp_lt_i32 s45, s64
	s_cselect_b32 s30, -1, 0
	v_cvt_f32_i32_e32 v0, s28
	v_mul_f32_e32 v13, v12, v0
	v_cmp_gt_f32_e32 vcc, s87, v13
	s_and_b64 s[26:27], vcc, exec
	s_cselect_b32 s26, 0xffffffc0, 0
	v_cndmask_b32_e32 v13, 0, v189, vcc
	v_fmac_f32_e32 v13, v12, v0
	v_exp_f32_e32 v0, v13
	s_waitcnt vmcnt(6)
; __device__ __forceinline__ float bflo(unsigned w) { return __uint_as_float(w << 16); }
; __device__ __forceinline__ float bfhi(unsigned w) { return __uint_as_float(w & 0xffff0000u); }
; __device__ __forceinline__ void retout_unit(CArgs& a, int l, unsigned char* lds, int u, const int tid) {
;     ...
; #pragma unroll 8
;       for (int m = 0; m < n; ++m) { const float wgt = exp2f(lg2 * 128.f * (float)(n - 1 - m)); const u32x4 v = *(const u32x4*)(KV + (size_t)(u - n + m) * 4096 + tid * 8);
;           r[0] += wgt * bflo(v.x); r[1] += wgt * bfhi(v.x); r[2] += wgt * bflo(v.y); r[3] += wgt * bfhi(v.y); r[4] += wgt * bflo(v.z); r[5] += wgt * bfhi(v.z); r[6] += wgt * bflo(v.w); r[7] += wgt * bfhi(v.w); }
	v_ldexp_f32 v0, v0, s26
	v_and_b32_e32 v0, s30, v0
	v_lshlrev_b32_e32 v14, 16, v212
	v_and_b32_e32 v15, 0xffff0000, v212
	v_pk_fma_f32 v[8:9], v[0:1], v[14:15], v[8:9] op_sel_hi:[0,1,1]
	v_lshlrev_b32_e32 v16, 16, v213
	v_and_b32_e32 v17, 0xffff0000, v213
	v_pk_fma_f32 v[6:7], v[0:1], v[16:17], v[6:7] op_sel_hi:[0,1,1]
	v_lshlrev_b32_e32 v18, 16, v214
	v_and_b32_e32 v19, 0xffff0000, v214
	v_pk_fma_f32 v[4:5], v[0:1], v[18:19], v[4:5] op_sel_hi:[0,1,1]
	v_lshlrev_b32_e32 v14, 16, v215
	v_and_b32_e32 v15, 0xffff0000, v215
	v_pk_fma_f32 v[2:3], v[0:1], v[14:15], v[2:3] op_sel_hi:[0,1,1]
	s_add_i32 s45, s65, 2
	s_sub_i32 s28, s59, s45
	s_cmp_lt_i32 s45, s64
	s_cselect_b32 s30, -1, 0
	v_cvt_f32_i32_e32 v0, s28
	v_mul_f32_e32 v13, v12, v0
	v_cmp_gt_f32_e32 vcc, s87, v13
	s_and_b64 s[26:27], vcc, exec
	s_cselect_b32 s26, 0xffffffc0, 0
	v_cndmask_b32_e32 v13, 0, v189, vcc
	v_fmac_f32_e32 v13, v12, v0
	v_exp_f32_e32 v0, v13
	s_waitcnt vmcnt(5)
	v_ldexp_f32 v0, v0, s26
	v_and_b32_e32 v0, s30, v0
	v_lshlrev_b32_e32 v14, 16, v216
	v_and_b32_e32 v15, 0xffff0000, v216
	v_pk_fma_f32 v[8:9], v[0:1], v[14:15], v[8:9] op_sel_hi:[0,1,1]
	v_lshlrev_b32_e32 v16, 16, v217
	v_and_b32_e32 v17, 0xffff0000, v217
	v_pk_fma_f32 v[6:7], v[0:1], v[16:17], v[6:7] op_sel_hi:[0,1,1]
	v_lshlrev_b32_e32 v18, 16, v218
	v_and_b32_e32 v19, 0xffff0000, v218
	v_pk_fma_f32 v[4:5], v[0:1], v[18:19], v[4:5] op_sel_hi:[0,1,1]
	v_lshlrev_b32_e32 v14, 16, v219
	v_and_b32_e32 v15, 0xffff0000, v219
	v_pk_fma_f32 v[2:3], v[0:1], v[14:15], v[2:3] op_sel_hi:[0,1,1]
	s_add_i32 s45, s65, 3
	s_sub_i32 s28, s59, s45
	s_cmp_lt_i32 s45, s64
	s_cselect_b32 s30, -1, 0
	v_cvt_f32_i32_e32 v0, s28
	v_mul_f32_e32 v13, v12, v0
	v_cmp_gt_f32_e32 vcc, s87, v13
	s_and_b64 s[26:27], vcc, exec
	s_cselect_b32 s26, 0xffffffc0, 0
	v_cndmask_b32_e32 v13, 0, v189, vcc
	v_fmac_f32_e32 v13, v12, v0
	v_exp_f32_e32 v0, v13
	s_waitcnt vmcnt(4)
	v_ldexp_f32 v0, v0, s26
	v_and_b32_e32 v0, s30, v0
	v_lshlrev_b32_e32 v14, 16, v220
	v_and_b32_e32 v15, 0xffff0000, v220
	v_pk_fma_f32 v[8:9], v[0:1], v[14:15], v[8:9] op_sel_hi:[0,1,1]
	v_lshlrev_b32_e32 v16, 16, v221
	v_and_b32_e32 v17, 0xffff0000, v221
	v_pk_fma_f32 v[6:7], v[0:1], v[16:17], v[6:7] op_sel_hi:[0,1,1]
	v_lshlrev_b32_e32 v18, 16, v222
	v_and_b32_e32 v19, 0xffff0000, v222
	v_pk_fma_f32 v[4:5], v[0:1], v[18:19], v[4:5] op_sel_hi:[0,1,1]
	v_lshlrev_b32_e32 v14, 16, v223
	v_and_b32_e32 v15, 0xffff0000, v223
	v_pk_fma_f32 v[2:3], v[0:1], v[14:15], v[2:3] op_sel_hi:[0,1,1]
	s_add_i32 s45, s65, 4
	s_sub_i32 s28, s59, s45
	s_cmp_lt_i32 s45, s64
	s_cselect_b32 s30, -1, 0
	v_cvt_f32_i32_e32 v0, s28
	v_mul_f32_e32 v13, v12, v0
	v_cmp_gt_f32_e32 vcc, s87, v13
	s_and_b64 s[26:27], vcc, exec
	s_cselect_b32 s26, 0xffffffc0, 0
	v_cndmask_b32_e32 v13, 0, v189, vcc
	v_fmac_f32_e32 v13, v12, v0
	v_exp_f32_e32 v0, v13
	s_waitcnt vmcnt(3)
	v_ldexp_f32 v0, v0, s26
	v_and_b32_e32 v0, s30, v0
	v_lshlrev_b32_e32 v14, 16, v224
	v_and_b32_e32 v15, 0xffff0000, v224
	v_pk_fma_f32 v[8:9], v[0:1], v[14:15], v[8:9] op_sel_hi:[0,1,1]
	v_lshlrev_b32_e32 v16, 16, v225
	v_and_b32_e32 v17, 0xffff0000, v225
	v_pk_fma_f32 v[6:7], v[0:1], v[16:17], v[6:7] op_sel_hi:[0,1,1]
	v_lshlrev_b32_e32 v18, 16, v226
	v_and_b32_e32 v19, 0xffff0000, v226
	v_pk_fma_f32 v[4:5], v[0:1], v[18:19], v[4:5] op_sel_hi:[0,1,1]
	v_lshlrev_b32_e32 v14, 16, v227
	v_and_b32_e32 v15, 0xffff0000, v227
	v_pk_fma_f32 v[2:3], v[0:1], v[14:15], v[2:3] op_sel_hi:[0,1,1]
	s_add_i32 s45, s65, 5
	s_sub_i32 s28, s59, s45
	s_cmp_lt_i32 s45, s64
	s_cselect_b32 s30, -1, 0
	v_cvt_f32_i32_e32 v0, s28
	v_mul_f32_e32 v13, v12, v0
	v_cmp_gt_f32_e32 vcc, s87, v13
	s_and_b64 s[26:27], vcc, exec
	s_cselect_b32 s26, 0xffffffc0, 0
	v_cndmask_b32_e32 v13, 0, v189, vcc
	v_fmac_f32_e32 v13, v12, v0
	v_exp_f32_e32 v0, v13
	s_waitcnt vmcnt(2)
	v_ldexp_f32 v0, v0, s26
	v_and_b32_e32 v0, s30, v0
	v_lshlrev_b32_e32 v14, 16, v228
	v_and_b32_e32 v15, 0xffff0000, v228
	v_pk_fma_f32 v[8:9], v[0:1], v[14:15], v[8:9] op_sel_hi:[0,1,1]
	v_lshlrev_b32_e32 v16, 16, v229
	v_and_b32_e32 v17, 0xffff0000, v229
	v_pk_fma_f32 v[6:7], v[0:1], v[16:17], v[6:7] op_sel_hi:[0,1,1]
	v_lshlrev_b32_e32 v18, 16, v230
	v_and_b32_e32 v19, 0xffff0000, v230
	v_pk_fma_f32 v[4:5], v[0:1], v[18:19], v[4:5] op_sel_hi:[0,1,1]
	v_lshlrev_b32_e32 v14, 16, v231
	v_and_b32_e32 v15, 0xffff0000, v231
	v_pk_fma_f32 v[2:3], v[0:1], v[14:15], v[2:3] op_sel_hi:[0,1,1]
	s_add_i32 s45, s65, 6
	s_sub_i32 s28, s59, s45
	s_cmp_lt_i32 s45, s64
	s_cselect_b32 s30, -1, 0
	v_cvt_f32_i32_e32 v0, s28
	v_mul_f32_e32 v13, v12, v0
	v_cmp_gt_f32_e32 vcc, s87, v13
	s_and_b64 s[26:27], vcc, exec
	s_cselect_b32 s26, 0xffffffc0, 0
	v_cndmask_b32_e32 v13, 0, v189, vcc
	v_fmac_f32_e32 v13, v12, v0
	v_exp_f32_e32 v0, v13
	s_waitcnt vmcnt(1)
	v_ldexp_f32 v0, v0, s26
	v_and_b32_e32 v0, s30, v0
	v_lshlrev_b32_e32 v14, 16, v232
	v_and_b32_e32 v15, 0xffff0000, v232
	v_pk_fma_f32 v[8:9], v[0:1], v[14:15], v[8:9] op_sel_hi:[0,1,1]
	v_lshlrev_b32_e32 v16, 16, v233
	v_and_b32_e32 v17, 0xffff0000, v233
	v_pk_fma_f32 v[6:7], v[0:1], v[16:17], v[6:7] op_sel_hi:[0,1,1]
	v_lshlrev_b32_e32 v18, 16, v234
	v_and_b32_e32 v19, 0xffff0000, v234
	v_pk_fma_f32 v[4:5], v[0:1], v[18:19], v[4:5] op_sel_hi:[0,1,1]
	v_lshlrev_b32_e32 v14, 16, v235
	v_and_b32_e32 v15, 0xffff0000, v235
	v_pk_fma_f32 v[2:3], v[0:1], v[14:15], v[2:3] op_sel_hi:[0,1,1]
	s_add_i32 s45, s65, 7
	s_sub_i32 s28, s59, s45
	s_cmp_lt_i32 s45, s64
	s_cselect_b32 s30, -1, 0
	v_cvt_f32_i32_e32 v0, s28
	v_mul_f32_e32 v13, v12, v0
	v_cmp_gt_f32_e32 vcc, s87, v13
	s_and_b64 s[26:27], vcc, exec
	s_cselect_b32 s26, 0xffffffc0, 0
	v_cndmask_b32_e32 v13, 0, v189, vcc
	v_fmac_f32_e32 v13, v12, v0
	v_exp_f32_e32 v0, v13
	s_waitcnt vmcnt(0)
	v_ldexp_f32 v0, v0, s26
	v_and_b32_e32 v0, s30, v0
	v_lshlrev_b32_e32 v14, 16, v236
	v_and_b32_e32 v15, 0xffff0000, v236
	v_pk_fma_f32 v[8:9], v[0:1], v[14:15], v[8:9] op_sel_hi:[0,1,1]
	v_lshlrev_b32_e32 v16, 16, v237
	v_and_b32_e32 v17, 0xffff0000, v237
	v_pk_fma_f32 v[6:7], v[0:1], v[16:17], v[6:7] op_sel_hi:[0,1,1]
	v_lshlrev_b32_e32 v18, 16, v238
	v_and_b32_e32 v19, 0xffff0000, v238
	v_pk_fma_f32 v[4:5], v[0:1], v[18:19], v[4:5] op_sel_hi:[0,1,1]
	v_lshlrev_b32_e32 v14, 16, v239
	v_and_b32_e32 v15, 0xffff0000, v239
	v_pk_fma_f32 v[2:3], v[0:1], v[14:15], v[2:3] op_sel_hi:[0,1,1]
	s_add_i32 s65, s65, 8
	s_cmp_lt_i32 s65, s64
	s_cbranch_scc1 .Lrt_batch

; #define PG8_STAGE(bufoff, gbase, voff) do { _Pragma("unroll") for (int _i = 0; _i < 2; ++_i) \
;         __builtin_amdgcn_global_load_lds((const unsigned*)((const char*)(gbase) + (voff)[_i]), (LAS unsigned*)(lds + (bufoff) + ldsw + _i * 8192), 16, 0, 0); } while (0)
; #define PG8_WAIT_V(n) asm volatile("s_waitcnt vmcnt(" #n ")" ::: "memory")
; #define PG8_BAR __builtin_amdgcn_s_barrier()
; template <class Epi, class Sched>
; __device__ __forceinline__ void gemm_phase(LAS unsigned char* lds, const Gemm g, const Sched& S, const Epi& E, const int tid) {
;     ...
;     for (int i = 0; i < 2; ++i) { int R, C; stage_rc(tid * 16 + i * 8192, R, C); const int Rb = Epi::PERM ? ((R & ~31) + perm32(R & 31)) : R;
;         voffA[i] = (unsigned)(R * P + C) * 2u; voffB[i] = (unsigned)(Rb * P + C) * 2u; }
;     const size_t kstep = (size_t)(BK * 2);
;     const size_t hstep = (size_t)HALF * P * 2;
;     const size_t tstep = 2 * hstep;
;     const unsigned ldsw = (unsigned)wid * 1024u;
;     const int aoff = lds_byte(wr * 64 + fr, fq * 8), boff = lds_byte(wc * 32 + fr, fq * 8);
;     ...
;     Unit cur, nxt; int ui = 0;
;     if (!S.next(0, cur)) return;
;     f32x4 acc[2][2][4][2];
; #pragma unroll
;     for (int a = 0; a < 2; ++a)
; #pragma unroll
;         for (int b = 0; b < 2; ++b)
; #pragma unroll
;             for (int m = 0; m < 4; ++m)
; #pragma unroll
;                 for (int n = 0; n < 2; ++n) acc[a][b][m][n] = (f32x4){0.f, 0.f, 0.f, 0.f};
;     bf16x8 At[4][2], B0[2][2], B1[2][2];
;     const char* cA = (const char*)g.A + (size_t)cur.pm * tstep + (size_t)cur.koff * 2; const char* cB = (const char*)g.Bt + (size_t)cur.pn * tstep + (size_t)cur.koff * 2;
;     E.prep(cur, lds + STAGE_BYTES, tid);
;     PG8_STAGE(PG8_SB(0, 0), cB, voffB); PG8_STAGE(PG8_SB(0, 1), cB + hstep, voffB); PG8_STAGE(PG8_SA(0, 0), cA, voffA); PG8_STAGE(PG8_SA(0, 1), cA + hstep, voffA);
;     if (wr == 1) PG8_BAR;
;     PG8_WAIT_V(2); PG8_BAR;
;     PG8_STAGE(PG8_SB(1, 0), cB + kstep, voffB); PG8_STAGE(PG8_SA(1, 0), cA + kstep, voffA); PG8_STAGE(PG8_SB(1, 1), cB + hstep + kstep, voffB);
.LBB0_404:
	s_mov_b64 s[84:85], s[12:13]
	s_add_u32 s18, s14, 0x2600000
	s_addc_u32 s19, s15, 0
	s_add_u32 s14, s14, 0x1fe00000
	s_addc_u32 s15, s15, 0
	s_and_b32 s59, s5, 3
	s_add_i32 m0, s44, 0x18000
	v_lshl_add_u64 v[8:9], v[8:9], 0, s[34:35]
	s_lshl_b32 s5, s4, 13
	s_lshl_b32 s8, s59, 12
	s_waitcnt vmcnt(2)
	s_barrier
	global_load_lds_dwordx4 v[8:9], off
	v_lshl_add_u64 v[6:7], v[6:7], 0, s[34:35]
	s_add_i32 m0, s44, 0x1a000
	s_add_i32 s60, s44, 0x8000
	s_add_i32 s61, s44, 0xa000
	global_load_lds_dwordx4 v[6:7], off
	v_lshl_add_u64 v[2:3], v[2:3], 0, s[34:35]
	s_mov_b32 m0, s60
	s_add_u32 s6, s52, 0xb0080
	global_load_lds_dwordx4 v[2:3], off
	v_lshl_add_u64 v[2:3], v[4:5], 0, s[34:35]
	s_mov_b32 m0, s61
	s_addc_u32 s7, s53, 0
	global_load_lds_dwordx4 v[2:3], off
	s_add_i32 m0, s44, 0x1c000
	v_lshl_add_u64 v[2:3], s[6:7], 0, v[0:1]
	global_load_lds_dwordx4 v[2:3], off
	v_lshl_add_u64 v[2:3], s[6:7], 0, v[130:131]
	s_add_i32 m0, s44, 0x1e000
	s_movk_i32 s9, 0xb00
	global_load_lds_dwordx4 v[2:3], off
	v_bfe_u32 v3, v10, 4, 2
	v_and_b32_e32 v2, 15, v10
	v_lshlrev_b32_e32 v4, 4, v3
	v_lshl_or_b32 v142, s4, 6, v2
	v_lshl_or_b32 v2, v2, 6, v4
	v_lshlrev_b32_e32 v4, 2, v10
	v_and_b32_e32 v4, 32, v4
	v_bitop3_b32 v5, v2, s5, v4 bitop3:0xde
	v_bitop3_b32 v143, s8, v2, v4 bitop3:0xf6
	v_lshlrev_b32_e32 v2, 2, v3
	v_lshl_or_b32 v144, s59, 5, v2
	v_cmp_eq_u32_e64 s[4:5], 0, v3
	v_ashrrev_i32_e64 v3, 31, s48
	v_mov_b32_e32 v2, s48
	v_readfirstlane_b32 s64, v3
	v_readfirstlane_b32 s63, v2
	v_lshrrev_b32_e32 v3, 1, v11
	v_mul_lo_u32 v2, v13, s9
	s_mov_b32 s8, 0xb000
	v_mad_u64_u32 v[2:3], s[6:7], v3, s8, v[2:3]
	v_or_b32_e32 v2, v2, v12
	v_add_lshl_u32 v2, v2, v14, 1
	v_mov_b32_e32 v3, v1
	s_mov_b64 s[26:27], 0xb0080
	v_lshl_add_u64 v[132:133], v[2:3], 0, s[26:27]
	v_lshrrev_b32_e32 v3, 1, v15
	v_mul_lo_u32 v2, v17, s9
	v_mad_u64_u32 v[2:3], s[6:7], v3, s8, v[2:3]
	s_waitcnt vmcnt(6)
	v_or_b32_e32 v2, v2, v16
	s_cmpk_lt_u32 s22, 0x100
	v_add_lshl_u32 v2, v2, v18, 1
	v_mov_b32_e32 v3, v1
	s_cselect_b64 s[22:23], -1, 0
	s_mov_b32 s62, 0
	s_ashr_i32 s65, s10, 31
	v_lshl_add_u64 v[134:135], v[2:3], 0, s[26:27]
	v_add_u32_e32 v145, 0, v5
	s_barrier
	s_branch .LBB0_407

; #define LAS __attribute__((address_space(3)))
; __device__ __forceinline__ unsigned cvt_pk_bf16(float lo, float hi) { unsigned r; asm volatile("v_cvt_pk_bf16_f32 %0, %1, %2" : "=v"(r) : "v"(lo), "v"(hi)); return r; }
;     __device__ __forceinline__ void operator()(const f32x4 (&acc)[2][2][4][2], const pg8::Unit& u, int wr, int wc, int fr, int fq, LAS unsigned char*) const {
;         const int row0 = u.pm * 256 + wr * 64 + fr, col0 = u.pn * 256 + wc * 32 + 4 * fq;
; #pragma unroll
;         for (int ai = 0; ai < 2; ++ai)
; #pragma unroll
;             for (int m = 0; m < 4; ++m) {
;                 const int row = row0 + ai * 128 + m * 16; const size_t off = (size_t)row * DM + col0; float q = 0.f;
; #pragma unroll
;                 for (int bj = 0; bj < 2; ++bj)
; #pragma unroll
;                     for (int n = 0; n < 2; ++n) { const size_t o = off + bj * 128 + n * 16; const f32x4 xv = *(const f32x4*)(xin + o) + acc[ai][bj][m][n]; *(f32x4*)(xout + o) = xv;
;                         q += (xv[0] * xv[0] + xv[1] * xv[1]) + (xv[2] * xv[2] + xv[3] * xv[3]);
;                         u32x2 w; w.x = cvt_pk_bf16(xv[0], xv[1]); w.y = cvt_pk_bf16(xv[2], xv[3]); *(u32x2*)(xb + o) = w; }
;                 q += __shfl_xor(q, 16); q += __shfl_xor(q, 32);
;                 if (fq == 0) ssq[(size_t)row * 16 + u.pn * 4 + wc] = q;
;             }
.LBB0_421:
	v_lshl_add_u32 v136, s68, 8, v142
	v_lshl_or_b32 v137, s28, 8, v144
	s_lshl_b32 s50, s28, 4
	s_lshl_b32 s51, s59, 2
	s_add_u32 s50, s50, s51
	v_lshl_add_u32 v139, v136, 10, v137
	v_lshl_add_u32 v140, v136, 6, s50
	v_lshlrev_b32_e32 v138, 2, v139
	v_lshlrev_b32_e32 v139, 1, v139
	v_xor_b32_e32 v141, 16, v187
	v_xor_b32_e32 v172, 32, v187
	v_lshlrev_b32_e32 v141, 2, v141
	v_lshlrev_b32_e32 v172, 2, v172
	global_load_dwordx4 v[198:201], v138, s[12:13]
	global_load_dwordx4 v[202:205], v138, s[12:13] offset:64
	global_load_dwordx4 v[206:209], v138, s[12:13] offset:512
	global_load_dwordx4 v[210:213], v138, s[12:13] offset:576
	v_add_u32_e32 v173, 0x10000, v138
	global_load_dwordx4 v[214:217], v173, s[12:13]
	global_load_dwordx4 v[218:221], v173, s[12:13] offset:64
	global_load_dwordx4 v[222:225], v173, s[12:13] offset:512
	global_load_dwordx4 v[226:229], v173, s[12:13] offset:576
	v_add_u32_e32 v173, 0x20000, v138
	global_load_dwordx4 v[156:159], v173, s[12:13]
	global_load_dwordx4 v[160:163], v173, s[12:13] offset:64
	global_load_dwordx4 v[164:167], v173, s[12:13] offset:512
	global_load_dwordx4 v[168:171], v173, s[12:13] offset:576
	v_mov_b32_e32 v174, v138
	v_mov_b32_e32 v175, v139
	v_mov_b32_e32 v176, v140
	s_waitcnt vmcnt(11)
	v_pk_add_f32 v[200:201], v[128:129], v[200:201]
	v_pk_add_f32 v[198:199], v[126:127], v[198:199]
	global_store_dwordx4 v174, v[198:201], s[84:85]
	v_mul_f32_e32 v178, v201, v201
	v_mul_f32_e32 v177, v199, v199
	v_fmac_f32_e32 v177, v198, v198
	v_fmac_f32_e32 v178, v200, v200
	v_cvt_pk_bf16_f32 v180, v198, v199
	v_cvt_pk_bf16_f32 v181, v200, v201
	v_add_f32_e32 v179, v177, v178
	global_store_dwordx2 v175, v[180:181], s[18:19]
	s_waitcnt vmcnt(12)
	v_pk_add_f32 v[204:205], v[124:125], v[204:205]
	v_pk_add_f32 v[202:203], v[122:123], v[202:203]
	global_store_dwordx4 v174, v[202:205], s[84:85] offset:64
	v_mul_f32_e32 v178, v205, v205
	v_mul_f32_e32 v177, v203, v203
	v_fmac_f32_e32 v177, v202, v202
	v_fmac_f32_e32 v178, v204, v204
	v_cvt_pk_bf16_f32 v182, v202, v203
	v_cvt_pk_bf16_f32 v183, v204, v205
	v_add_f32_e32 v177, v177, v178
	v_add_f32_e32 v179, v179, v177
	global_store_dwordx2 v175, v[182:183], s[18:19] offset:32
	s_waitcnt vmcnt(13)
	v_pk_add_f32 v[208:209], v[120:121], v[208:209]
	v_pk_add_f32 v[206:207], v[118:119], v[206:207]
	global_store_dwordx4 v174, v[206:209], s[84:85] offset:512
	v_mul_f32_e32 v178, v209, v209
	v_mul_f32_e32 v177, v207, v207
	v_fmac_f32_e32 v177, v206, v206
	v_fmac_f32_e32 v178, v208, v208
	v_cvt_pk_bf16_f32 v180, v206, v207
	v_cvt_pk_bf16_f32 v181, v208, v209
	v_add_f32_e32 v177, v177, v178
	v_add_f32_e32 v179, v179, v177
	global_store_dwordx2 v175, v[180:181], s[18:19] offset:256
	s_waitcnt vmcnt(14)
	v_pk_add_f32 v[212:213], v[116:117], v[212:213]
	v_pk_add_f32 v[210:211], v[114:115], v[210:211]
	global_store_dwordx4 v174, v[210:213], s[84:85] offset:576
	v_mul_f32_e32 v178, v213, v213
	v_mul_f32_e32 v177, v211, v211
	v_fmac_f32_e32 v177, v210, v210
	v_fmac_f32_e32 v178, v212, v212
	v_cvt_pk_bf16_f32 v182, v210, v211
	v_cvt_pk_bf16_f32 v183, v212, v213
	v_add_f32_e32 v177, v177, v178
	v_add_f32_e32 v179, v179, v177
	global_store_dwordx2 v175, v[182:183], s[18:19] offset:288
	ds_bpermute_b32 v177, v141, v179
	s_waitcnt lgkmcnt(0)
	v_add_f32_e32 v179, v179, v177
	ds_bpermute_b32 v178, v172, v179
	s_waitcnt lgkmcnt(0)
	v_add_f32_e32 v179, v179, v178
	s_and_saveexec_b64 s[52:53], s[4:5]
	global_store_dword v176, v179, s[14:15]
	s_mov_b64 exec, s[52:53]
	v_add_u32_e32 v173, 0x30000, v138
	global_load_dwordx4 v[198:201], v173, s[12:13]
	global_load_dwordx4 v[202:205], v173, s[12:13] offset:64
	global_load_dwordx4 v[206:209], v173, s[12:13] offset:512
	global_load_dwordx4 v[210:213], v173, s[12:13] offset:576
	v_add_u32_e32 v174, 0x10000, v138
	v_add_u32_e32 v175, 0x8000, v139
	v_add_u32_e32 v176, 0x400, v140
	s_waitcnt vmcnt(20)
	v_pk_add_f32 v[216:217], v[112:113], v[216:217]
	v_pk_add_f32 v[214:215], v[110:111], v[214:215]
	global_store_dwordx4 v174, v[214:217], s[84:85]
	v_mul_f32_e32 v178, v217, v217
	v_mul_f32_e32 v177, v215, v215
	v_fmac_f32_e32 v177, v214, v214
	v_fmac_f32_e32 v178, v216, v216
	v_cvt_pk_bf16_f32 v180, v214, v215
	v_cvt_pk_bf16_f32 v181, v216, v217
	v_add_f32_e32 v179, v177, v178
	global_store_dwordx2 v175, v[180:181], s[18:19]
	s_waitcnt vmcnt(21)
	v_pk_add_f32 v[220:221], v[108:109], v[220:221]
	v_pk_add_f32 v[218:219], v[106:107], v[218:219]
	global_store_dwordx4 v174, v[218:221], s[84:85] offset:64
	v_mul_f32_e32 v178, v221, v221
	v_mul_f32_e32 v177, v219, v219
	v_fmac_f32_e32 v177, v218, v218
	v_fmac_f32_e32 v178, v220, v220
	v_cvt_pk_bf16_f32 v182, v218, v219
	v_cvt_pk_bf16_f32 v183, v220, v221
	v_add_f32_e32 v177, v177, v178
	v_add_f32_e32 v179, v179, v177
	global_store_dwordx2 v175, v[182:183], s[18:19] offset:32
	s_waitcnt vmcnt(22)
	v_pk_add_f32 v[224:225], v[104:105], v[224:225]
	v_pk_add_f32 v[222:223], v[102:103], v[222:223]
	global_store_dwordx4 v174, v[222:225], s[84:85] offset:512
	v_mul_f32_e32 v178, v225, v225
	v_mul_f32_e32 v177, v223, v223
	v_fmac_f32_e32 v177, v222, v222
	v_fmac_f32_e32 v178, v224, v224
	v_cvt_pk_bf16_f32 v180, v222, v223
	v_cvt_pk_bf16_f32 v181, v224, v225
	v_add_f32_e32 v177, v177, v178
	v_add_f32_e32 v179, v179, v177
	global_store_dwordx2 v175, v[180:181], s[18:19] offset:256
	s_waitcnt vmcnt(23)
	v_pk_add_f32 v[228:229], v[100:101], v[228:229]
	v_pk_add_f32 v[226:227], v[98:99], v[226:227]
	global_store_dwordx4 v174, v[226:229], s[84:85] offset:576
	v_mul_f32_e32 v178, v229, v229
	v_mul_f32_e32 v177, v227, v227
	v_fmac_f32_e32 v177, v226, v226
	v_fmac_f32_e32 v178, v228, v228
	v_cvt_pk_bf16_f32 v182, v226, v227
	v_cvt_pk_bf16_f32 v183, v228, v229
	v_add_f32_e32 v177, v177, v178
	v_add_f32_e32 v179, v179, v177
	global_store_dwordx2 v175, v[182:183], s[18:19] offset:288
	ds_bpermute_b32 v177, v141, v179
	s_waitcnt lgkmcnt(0)
; #define LAS __attribute__((address_space(3)))
; __device__ __forceinline__ unsigned cvt_pk_bf16(float lo, float hi) { unsigned r; asm volatile("v_cvt_pk_bf16_f32 %0, %1, %2" : "=v"(r) : "v"(lo), "v"(hi)); return r; }
;     __device__ __forceinline__ void operator()(const f32x4 (&acc)[2][2][4][2], const pg8::Unit& u, int wr, int wc, int fr, int fq, LAS unsigned char*) const {
;         const int row0 = u.pm * 256 + wr * 64 + fr, col0 = u.pn * 256 + wc * 32 + 4 * fq;
; #pragma unroll
;         for (int ai = 0; ai < 2; ++ai)
; #pragma unroll
;             for (int m = 0; m < 4; ++m) {
;                 const int row = row0 + ai * 128 + m * 16; const size_t off = (size_t)row * DM + col0; float q = 0.f;
; #pragma unroll
;                 for (int bj = 0; bj < 2; ++bj)
; #pragma unroll
;                     for (int n = 0; n < 2; ++n) { const size_t o = off + bj * 128 + n * 16; const f32x4 xv = *(const f32x4*)(xin + o) + acc[ai][bj][m][n]; *(f32x4*)(xout + o) = xv;
;                         q += (xv[0] * xv[0] + xv[1] * xv[1]) + (xv[2] * xv[2] + xv[3] * xv[3]);
;                         u32x2 w; w.x = cvt_pk_bf16(xv[0], xv[1]); w.y = cvt_pk_bf16(xv[2], xv[3]); *(u32x2*)(xb + o) = w; }
;                 q += __shfl_xor(q, 16); q += __shfl_xor(q, 32);
;                 if (fq == 0) ssq[(size_t)row * 16 + u.pn * 4 + wc] = q;
;             }
	v_add_f32_e32 v179, v179, v177
	ds_bpermute_b32 v178, v172, v179
	s_waitcnt lgkmcnt(0)
	v_add_f32_e32 v179, v179, v178
	s_and_saveexec_b64 s[52:53], s[4:5]
	global_store_dword v176, v179, s[14:15]
	s_mov_b64 exec, s[52:53]
	v_add_u32_e32 v173, 0x80000, v138
	global_load_dwordx4 v[214:217], v173, s[12:13]
	global_load_dwordx4 v[218:221], v173, s[12:13] offset:64
	global_load_dwordx4 v[222:225], v173, s[12:13] offset:512
	global_load_dwordx4 v[226:229], v173, s[12:13] offset:576
	v_add_u32_e32 v174, 0x20000, v138
	v_add_u32_e32 v175, 0x10000, v139
	v_add_u32_e32 v176, 0x800, v140
	s_waitcnt vmcnt(29)
	v_pk_add_f32 v[158:159], v[96:97], v[158:159]
	v_pk_add_f32 v[156:157], v[94:95], v[156:157]
	global_store_dwordx4 v174, v[156:159], s[84:85]
	v_mul_f32_e32 v178, v159, v159
	v_mul_f32_e32 v177, v157, v157
	v_fmac_f32_e32 v177, v156, v156
	v_fmac_f32_e32 v178, v158, v158
	v_cvt_pk_bf16_f32 v180, v156, v157
	v_cvt_pk_bf16_f32 v181, v158, v159
	v_add_f32_e32 v179, v177, v178
	global_store_dwordx2 v175, v[180:181], s[18:19]
	s_waitcnt vmcnt(30)
	v_pk_add_f32 v[162:163], v[92:93], v[162:163]
	v_pk_add_f32 v[160:161], v[90:91], v[160:161]
	global_store_dwordx4 v174, v[160:163], s[84:85] offset:64
	v_mul_f32_e32 v178, v163, v163
	v_mul_f32_e32 v177, v161, v161
	v_fmac_f32_e32 v177, v160, v160
	v_fmac_f32_e32 v178, v162, v162
	v_cvt_pk_bf16_f32 v182, v160, v161
	v_cvt_pk_bf16_f32 v183, v162, v163
	v_add_f32_e32 v177, v177, v178
	v_add_f32_e32 v179, v179, v177
	global_store_dwordx2 v175, v[182:183], s[18:19] offset:32
	s_waitcnt vmcnt(31)
	v_pk_add_f32 v[166:167], v[88:89], v[166:167]
	v_pk_add_f32 v[164:165], v[86:87], v[164:165]
	global_store_dwordx4 v174, v[164:167], s[84:85] offset:512
	v_mul_f32_e32 v178, v167, v167
	v_mul_f32_e32 v177, v165, v165
	v_fmac_f32_e32 v177, v164, v164
	v_fmac_f32_e32 v178, v166, v166
	v_cvt_pk_bf16_f32 v180, v164, v165
	v_cvt_pk_bf16_f32 v181, v166, v167
	v_add_f32_e32 v177, v177, v178
	v_add_f32_e32 v179, v179, v177
	global_store_dwordx2 v175, v[180:181], s[18:19] offset:256
	s_waitcnt vmcnt(32)
	v_pk_add_f32 v[170:171], v[84:85], v[170:171]
	v_pk_add_f32 v[168:169], v[82:83], v[168:169]
	global_store_dwordx4 v174, v[168:171], s[84:85] offset:576
	v_mul_f32_e32 v178, v171, v171
	v_mul_f32_e32 v177, v169, v169
	v_fmac_f32_e32 v177, v168, v168
	v_fmac_f32_e32 v178, v170, v170
	v_cvt_pk_bf16_f32 v182, v168, v169
	v_cvt_pk_bf16_f32 v183, v170, v171
	v_add_f32_e32 v177, v177, v178
	v_add_f32_e32 v179, v179, v177
	global_store_dwordx2 v175, v[182:183], s[18:19] offset:288
	ds_bpermute_b32 v177, v141, v179
	s_waitcnt lgkmcnt(0)
	v_add_f32_e32 v179, v179, v177
	ds_bpermute_b32 v178, v172, v179
	s_waitcnt lgkmcnt(0)
	v_add_f32_e32 v179, v179, v178
	s_and_saveexec_b64 s[52:53], s[4:5]
	global_store_dword v176, v179, s[14:15]
	s_mov_b64 exec, s[52:53]
	v_add_u32_e32 v173, 0x90000, v138
	global_load_dwordx4 v[156:159], v173, s[12:13]
	global_load_dwordx4 v[160:163], v173, s[12:13] offset:64
	global_load_dwordx4 v[164:167], v173, s[12:13] offset:512
	global_load_dwordx4 v[168:171], v173, s[12:13] offset:576
	v_add_u32_e32 v174, 0x30000, v138
	v_add_u32_e32 v175, 0x18000, v139
	v_add_u32_e32 v176, 0xc00, v140
	s_waitcnt vmcnt(29)
	v_pk_add_f32 v[200:201], v[80:81], v[200:201]
	v_pk_add_f32 v[198:199], v[78:79], v[198:199]
	global_store_dwordx4 v174, v[198:201], s[84:85]
	v_mul_f32_e32 v178, v201, v201
	v_mul_f32_e32 v177, v199, v199
	v_fmac_f32_e32 v177, v198, v198
	v_fmac_f32_e32 v178, v200, v200
	v_cvt_pk_bf16_f32 v180, v198, v199
	v_cvt_pk_bf16_f32 v181, v200, v201
	v_add_f32_e32 v179, v177, v178
	global_store_dwordx2 v175, v[180:181], s[18:19]
	s_waitcnt vmcnt(30)
	v_pk_add_f32 v[204:205], v[76:77], v[204:205]
	v_pk_add_f32 v[202:203], v[74:75], v[202:203]
	global_store_dwordx4 v174, v[202:205], s[84:85] offset:64
	v_mul_f32_e32 v178, v205, v205
	v_mul_f32_e32 v177, v203, v203
	v_fmac_f32_e32 v177, v202, v202
	v_fmac_f32_e32 v178, v204, v204
	v_cvt_pk_bf16_f32 v182, v202, v203
	v_cvt_pk_bf16_f32 v183, v204, v205
	v_add_f32_e32 v177, v177, v178
	v_add_f32_e32 v179, v179, v177
	global_store_dwordx2 v175, v[182:183], s[18:19] offset:32
	s_waitcnt vmcnt(31)
	v_pk_add_f32 v[208:209], v[72:73], v[208:209]
	v_pk_add_f32 v[206:207], v[70:71], v[206:207]
	global_store_dwordx4 v174, v[206:209], s[84:85] offset:512
	v_mul_f32_e32 v178, v209, v209
	v_mul_f32_e32 v177, v207, v207
	v_fmac_f32_e32 v177, v206, v206
	v_fmac_f32_e32 v178, v208, v208
	v_cvt_pk_bf16_f32 v180, v206, v207
	v_cvt_pk_bf16_f32 v181, v208, v209
	v_add_f32_e32 v177, v177, v178
	v_add_f32_e32 v179, v179, v177
	global_store_dwordx2 v175, v[180:181], s[18:19] offset:256
	s_waitcnt vmcnt(32)
	v_pk_add_f32 v[212:213], v[68:69], v[212:213]
	v_pk_add_f32 v[210:211], v[66:67], v[210:211]
	global_store_dwordx4 v174, v[210:213], s[84:85] offset:576
	v_mul_f32_e32 v178, v213, v213
	v_mul_f32_e32 v177, v211, v211
	v_fmac_f32_e32 v177, v210, v210
	v_fmac_f32_e32 v178, v212, v212
	v_cvt_pk_bf16_f32 v182, v210, v211
	v_cvt_pk_bf16_f32 v183, v212, v213
	v_add_f32_e32 v177, v177, v178
	v_add_f32_e32 v179, v179, v177
	global_store_dwordx2 v175, v[182:183], s[18:19] offset:288
	ds_bpermute_b32 v177, v141, v179
	s_waitcnt lgkmcnt(0)
	v_add_f32_e32 v179, v179, v177
	ds_bpermute_b32 v178, v172, v179
	s_waitcnt lgkmcnt(0)
	v_add_f32_e32 v179, v179, v178
	s_and_saveexec_b64 s[52:53], s[4:5]
	global_store_dword v176, v179, s[14:15]
	s_mov_b64 exec, s[52:53]
	v_add_u32_e32 v173, 0xa0000, v138
	global_load_dwordx4 v[198:201], v173, s[12:13]
	global_load_dwordx4 v[202:205], v173, s[12:13] offset:64
	global_load_dwordx4 v[206:209], v173, s[12:13] offset:512
	global_load_dwordx4 v[210:213], v173, s[12:13] offset:576
	v_add_u32_e32 v174, 0x80000, v138
	v_add_u32_e32 v175, 0x40000, v139
	v_add_u32_e32 v176, 0x2000, v140
	s_waitcnt vmcnt(29)
; #define LAS __attribute__((address_space(3)))
; __device__ __forceinline__ unsigned cvt_pk_bf16(float lo, float hi) { unsigned r; asm volatile("v_cvt_pk_bf16_f32 %0, %1, %2" : "=v"(r) : "v"(lo), "v"(hi)); return r; }
;     __device__ __forceinline__ void operator()(const f32x4 (&acc)[2][2][4][2], const pg8::Unit& u, int wr, int wc, int fr, int fq, LAS unsigned char*) const {
;         const int row0 = u.pm * 256 + wr * 64 + fr, col0 = u.pn * 256 + wc * 32 + 4 * fq;
; #pragma unroll
;         for (int ai = 0; ai < 2; ++ai)
; #pragma unroll
;             for (int m = 0; m < 4; ++m) {
;                 const int row = row0 + ai * 128 + m * 16; const size_t off = (size_t)row * DM + col0; float q = 0.f;
; #pragma unroll
;                 for (int bj = 0; bj < 2; ++bj)
; #pragma unroll
;                     for (int n = 0; n < 2; ++n) { const size_t o = off + bj * 128 + n * 16; const f32x4 xv = *(const f32x4*)(xin + o) + acc[ai][bj][m][n]; *(f32x4*)(xout + o) = xv;
;                         q += (xv[0] * xv[0] + xv[1] * xv[1]) + (xv[2] * xv[2] + xv[3] * xv[3]);
;                         u32x2 w; w.x = cvt_pk_bf16(xv[0], xv[1]); w.y = cvt_pk_bf16(xv[2], xv[3]); *(u32x2*)(xb + o) = w; }
;                 q += __shfl_xor(q, 16); q += __shfl_xor(q, 32);
;                 if (fq == 0) ssq[(size_t)row * 16 + u.pn * 4 + wc] = q;
;             }
	v_pk_add_f32 v[216:217], v[64:65], v[216:217]
	v_pk_add_f32 v[214:215], v[62:63], v[214:215]
	global_store_dwordx4 v174, v[214:217], s[84:85]
	v_mul_f32_e32 v178, v217, v217
	v_mul_f32_e32 v177, v215, v215
	v_fmac_f32_e32 v177, v214, v214
	v_fmac_f32_e32 v178, v216, v216
	v_cvt_pk_bf16_f32 v180, v214, v215
	v_cvt_pk_bf16_f32 v181, v216, v217
	v_add_f32_e32 v179, v177, v178
	global_store_dwordx2 v175, v[180:181], s[18:19]
	s_waitcnt vmcnt(30)
	v_pk_add_f32 v[220:221], v[60:61], v[220:221]
	v_pk_add_f32 v[218:219], v[58:59], v[218:219]
	global_store_dwordx4 v174, v[218:221], s[84:85] offset:64
	v_mul_f32_e32 v178, v221, v221
	v_mul_f32_e32 v177, v219, v219
	v_fmac_f32_e32 v177, v218, v218
	v_fmac_f32_e32 v178, v220, v220
	v_cvt_pk_bf16_f32 v182, v218, v219
	v_cvt_pk_bf16_f32 v183, v220, v221
	v_add_f32_e32 v177, v177, v178
	v_add_f32_e32 v179, v179, v177
	global_store_dwordx2 v175, v[182:183], s[18:19] offset:32
	s_waitcnt vmcnt(31)
	v_pk_add_f32 v[224:225], v[56:57], v[224:225]
	v_pk_add_f32 v[222:223], v[54:55], v[222:223]
	global_store_dwordx4 v174, v[222:225], s[84:85] offset:512
	v_mul_f32_e32 v178, v225, v225
	v_mul_f32_e32 v177, v223, v223
	v_fmac_f32_e32 v177, v222, v222
	v_fmac_f32_e32 v178, v224, v224
	v_cvt_pk_bf16_f32 v180, v222, v223
	v_cvt_pk_bf16_f32 v181, v224, v225
	v_add_f32_e32 v177, v177, v178
	v_add_f32_e32 v179, v179, v177
	global_store_dwordx2 v175, v[180:181], s[18:19] offset:256
	s_waitcnt vmcnt(32)
	v_pk_add_f32 v[228:229], v[52:53], v[228:229]
	v_pk_add_f32 v[226:227], v[50:51], v[226:227]
	global_store_dwordx4 v174, v[226:229], s[84:85] offset:576
	v_mul_f32_e32 v178, v229, v229
	v_mul_f32_e32 v177, v227, v227
	v_fmac_f32_e32 v177, v226, v226
	v_fmac_f32_e32 v178, v228, v228
	v_cvt_pk_bf16_f32 v182, v226, v227
	v_cvt_pk_bf16_f32 v183, v228, v229
	v_add_f32_e32 v177, v177, v178
	v_add_f32_e32 v179, v179, v177
	global_store_dwordx2 v175, v[182:183], s[18:19] offset:288
	ds_bpermute_b32 v177, v141, v179
	s_waitcnt lgkmcnt(0)
	v_add_f32_e32 v179, v179, v177
	ds_bpermute_b32 v178, v172, v179
	s_waitcnt lgkmcnt(0)
	v_add_f32_e32 v179, v179, v178
	s_and_saveexec_b64 s[52:53], s[4:5]
	global_store_dword v176, v179, s[14:15]
	s_mov_b64 exec, s[52:53]
	v_add_u32_e32 v173, 0xb0000, v138
	global_load_dwordx4 v[214:217], v173, s[12:13]
	global_load_dwordx4 v[218:221], v173, s[12:13] offset:64
	global_load_dwordx4 v[222:225], v173, s[12:13] offset:512
	global_load_dwordx4 v[226:229], v173, s[12:13] offset:576
	v_add_u32_e32 v174, 0x90000, v138
	v_add_u32_e32 v175, 0x48000, v139
	v_add_u32_e32 v176, 0x2400, v140
	s_waitcnt vmcnt(29)
	v_pk_add_f32 v[158:159], v[48:49], v[158:159]
	v_pk_add_f32 v[156:157], v[46:47], v[156:157]
	global_store_dwordx4 v174, v[156:159], s[84:85]
	v_mul_f32_e32 v178, v159, v159
	v_mul_f32_e32 v177, v157, v157
	v_fmac_f32_e32 v177, v156, v156
	v_fmac_f32_e32 v178, v158, v158
	v_cvt_pk_bf16_f32 v180, v156, v157
	v_cvt_pk_bf16_f32 v181, v158, v159
	v_add_f32_e32 v179, v177, v178
	global_store_dwordx2 v175, v[180:181], s[18:19]
	s_waitcnt vmcnt(30)
	v_pk_add_f32 v[162:163], v[44:45], v[162:163]
	v_pk_add_f32 v[160:161], v[42:43], v[160:161]
	global_store_dwordx4 v174, v[160:163], s[84:85] offset:64
	v_mul_f32_e32 v178, v163, v163
	v_mul_f32_e32 v177, v161, v161
	v_fmac_f32_e32 v177, v160, v160
	v_fmac_f32_e32 v178, v162, v162
	v_cvt_pk_bf16_f32 v182, v160, v161
	v_cvt_pk_bf16_f32 v183, v162, v163
	v_add_f32_e32 v177, v177, v178
	v_add_f32_e32 v179, v179, v177
	global_store_dwordx2 v175, v[182:183], s[18:19] offset:32
	s_waitcnt vmcnt(31)
	v_pk_add_f32 v[166:167], v[40:41], v[166:167]
	v_pk_add_f32 v[164:165], v[38:39], v[164:165]
	global_store_dwordx4 v174, v[164:167], s[84:85] offset:512
	v_mul_f32_e32 v178, v167, v167
	v_mul_f32_e32 v177, v165, v165
	v_fmac_f32_e32 v177, v164, v164
	v_fmac_f32_e32 v178, v166, v166
	v_cvt_pk_bf16_f32 v180, v164, v165
	v_cvt_pk_bf16_f32 v181, v166, v167
	v_add_f32_e32 v177, v177, v178
	v_add_f32_e32 v179, v179, v177
	global_store_dwordx2 v175, v[180:181], s[18:19] offset:256
	s_waitcnt vmcnt(32)
	v_pk_add_f32 v[170:171], v[36:37], v[170:171]
	v_pk_add_f32 v[168:169], v[34:35], v[168:169]
	global_store_dwordx4 v174, v[168:171], s[84:85] offset:576
	v_mul_f32_e32 v178, v171, v171
	v_mul_f32_e32 v177, v169, v169
	v_fmac_f32_e32 v177, v168, v168
	v_fmac_f32_e32 v178, v170, v170
	v_cvt_pk_bf16_f32 v182, v168, v169
	v_cvt_pk_bf16_f32 v183, v170, v171
	v_add_f32_e32 v177, v177, v178
	v_add_f32_e32 v179, v179, v177
	global_store_dwordx2 v175, v[182:183], s[18:19] offset:288
	ds_bpermute_b32 v177, v141, v179
	s_waitcnt lgkmcnt(0)
	v_add_f32_e32 v179, v179, v177
	ds_bpermute_b32 v178, v172, v179
	s_waitcnt lgkmcnt(0)
	v_add_f32_e32 v179, v179, v178
	s_and_saveexec_b64 s[52:53], s[4:5]
	global_store_dword v176, v179, s[14:15]
	s_mov_b64 exec, s[52:53]
	v_add_u32_e32 v174, 0xa0000, v138
	v_add_u32_e32 v175, 0x50000, v139
	v_add_u32_e32 v176, 0x2800, v140
	s_waitcnt vmcnt(25)
; #define LAS __attribute__((address_space(3)))
; __device__ __forceinline__ unsigned cvt_pk_bf16(float lo, float hi) { unsigned r; asm volatile("v_cvt_pk_bf16_f32 %0, %1, %2" : "=v"(r) : "v"(lo), "v"(hi)); return r; }
;     __device__ __forceinline__ void operator()(const f32x4 (&acc)[2][2][4][2], const pg8::Unit& u, int wr, int wc, int fr, int fq, LAS unsigned char*) const {
;         const int row0 = u.pm * 256 + wr * 64 + fr, col0 = u.pn * 256 + wc * 32 + 4 * fq;
; #pragma unroll
;         for (int ai = 0; ai < 2; ++ai)
; #pragma unroll
;             for (int m = 0; m < 4; ++m) {
;                 const int row = row0 + ai * 128 + m * 16; const size_t off = (size_t)row * DM + col0; float q = 0.f;
; #pragma unroll
;                 for (int bj = 0; bj < 2; ++bj)
; #pragma unroll
;                     for (int n = 0; n < 2; ++n) { const size_t o = off + bj * 128 + n * 16; const f32x4 xv = *(const f32x4*)(xin + o) + acc[ai][bj][m][n]; *(f32x4*)(xout + o) = xv;
;                         q += (xv[0] * xv[0] + xv[1] * xv[1]) + (xv[2] * xv[2] + xv[3] * xv[3]);
;                         u32x2 w; w.x = cvt_pk_bf16(xv[0], xv[1]); w.y = cvt_pk_bf16(xv[2], xv[3]); *(u32x2*)(xb + o) = w; }
;                 q += __shfl_xor(q, 16); q += __shfl_xor(q, 32);
;                 if (fq == 0) ssq[(size_t)row * 16 + u.pn * 4 + wc] = q;
;             }
	v_pk_add_f32 v[200:201], v[32:33], v[200:201]
	v_pk_add_f32 v[198:199], v[30:31], v[198:199]
	global_store_dwordx4 v174, v[198:201], s[84:85]
	v_mul_f32_e32 v178, v201, v201
	v_mul_f32_e32 v177, v199, v199
	v_fmac_f32_e32 v177, v198, v198
	v_fmac_f32_e32 v178, v200, v200
	v_cvt_pk_bf16_f32 v180, v198, v199
	v_cvt_pk_bf16_f32 v181, v200, v201
	v_add_f32_e32 v179, v177, v178
	global_store_dwordx2 v175, v[180:181], s[18:19]
	s_waitcnt vmcnt(26)
	v_pk_add_f32 v[204:205], v[28:29], v[204:205]
	v_pk_add_f32 v[202:203], v[26:27], v[202:203]
	global_store_dwordx4 v174, v[202:205], s[84:85] offset:64
	v_mul_f32_e32 v178, v205, v205
	v_mul_f32_e32 v177, v203, v203
	v_fmac_f32_e32 v177, v202, v202
	v_fmac_f32_e32 v178, v204, v204
	v_cvt_pk_bf16_f32 v182, v202, v203
	v_cvt_pk_bf16_f32 v183, v204, v205
	v_add_f32_e32 v177, v177, v178
	v_add_f32_e32 v179, v179, v177
	global_store_dwordx2 v175, v[182:183], s[18:19] offset:32
	s_waitcnt vmcnt(27)
	v_pk_add_f32 v[208:209], v[24:25], v[208:209]
	v_pk_add_f32 v[206:207], v[22:23], v[206:207]
	global_store_dwordx4 v174, v[206:209], s[84:85] offset:512
	v_mul_f32_e32 v178, v209, v209
	v_mul_f32_e32 v177, v207, v207
	v_fmac_f32_e32 v177, v206, v206
	v_fmac_f32_e32 v178, v208, v208
	v_cvt_pk_bf16_f32 v180, v206, v207
	v_cvt_pk_bf16_f32 v181, v208, v209
	v_add_f32_e32 v177, v177, v178
	v_add_f32_e32 v179, v179, v177
	global_store_dwordx2 v175, v[180:181], s[18:19] offset:256
	s_waitcnt vmcnt(28)
	v_pk_add_f32 v[212:213], v[20:21], v[212:213]
	v_pk_add_f32 v[210:211], v[18:19], v[210:211]
	global_store_dwordx4 v174, v[210:213], s[84:85] offset:576
	v_mul_f32_e32 v178, v213, v213
	v_mul_f32_e32 v177, v211, v211
	v_fmac_f32_e32 v177, v210, v210
	v_fmac_f32_e32 v178, v212, v212
	v_cvt_pk_bf16_f32 v182, v210, v211
	v_cvt_pk_bf16_f32 v183, v212, v213
	v_add_f32_e32 v177, v177, v178
	v_add_f32_e32 v179, v179, v177
	global_store_dwordx2 v175, v[182:183], s[18:19] offset:288
	ds_bpermute_b32 v177, v141, v179
	s_waitcnt lgkmcnt(0)
	v_add_f32_e32 v179, v179, v177
	ds_bpermute_b32 v178, v172, v179
	s_waitcnt lgkmcnt(0)
	v_add_f32_e32 v179, v179, v178
	s_and_saveexec_b64 s[52:53], s[4:5]
	global_store_dword v176, v179, s[14:15]
	s_mov_b64 exec, s[52:53]
	v_add_u32_e32 v174, 0xb0000, v138
	v_add_u32_e32 v175, 0x58000, v139
	v_add_u32_e32 v176, 0x2c00, v140
	s_waitcnt vmcnt(21)
	v_pk_add_f32 v[216:217], v[16:17], v[216:217]
	v_pk_add_f32 v[214:215], v[14:15], v[214:215]
	global_store_dwordx4 v174, v[214:217], s[84:85]
	v_mul_f32_e32 v178, v217, v217
	v_mul_f32_e32 v177, v215, v215
	v_fmac_f32_e32 v177, v214, v214
	v_fmac_f32_e32 v178, v216, v216
	v_cvt_pk_bf16_f32 v180, v214, v215
	v_cvt_pk_bf16_f32 v181, v216, v217
	v_add_f32_e32 v179, v177, v178
	global_store_dwordx2 v175, v[180:181], s[18:19]
	s_waitcnt vmcnt(22)
	v_pk_add_f32 v[220:221], v[12:13], v[220:221]
	v_pk_add_f32 v[218:219], v[10:11], v[218:219]
	global_store_dwordx4 v174, v[218:221], s[84:85] offset:64
	v_mul_f32_e32 v178, v221, v221
	v_mul_f32_e32 v177, v219, v219
	v_fmac_f32_e32 v177, v218, v218
	v_fmac_f32_e32 v178, v220, v220
	v_cvt_pk_bf16_f32 v182, v218, v219
	v_cvt_pk_bf16_f32 v183, v220, v221
	v_add_f32_e32 v177, v177, v178
	v_add_f32_e32 v179, v179, v177
	global_store_dwordx2 v175, v[182:183], s[18:19] offset:32
	s_waitcnt vmcnt(23)
	v_pk_add_f32 v[224:225], v[8:9], v[224:225]
	v_pk_add_f32 v[222:223], v[6:7], v[222:223]
	global_store_dwordx4 v174, v[222:225], s[84:85] offset:512
	v_mul_f32_e32 v178, v225, v225
	v_mul_f32_e32 v177, v223, v223
	v_fmac_f32_e32 v177, v222, v222
	v_fmac_f32_e32 v178, v224, v224
	v_cvt_pk_bf16_f32 v180, v222, v223
	v_cvt_pk_bf16_f32 v181, v224, v225
	v_add_f32_e32 v177, v177, v178
	v_add_f32_e32 v179, v179, v177
	global_store_dwordx2 v175, v[180:181], s[18:19] offset:256
	s_waitcnt vmcnt(24)
	v_pk_add_f32 v[228:229], v[4:5], v[228:229]
	v_pk_add_f32 v[226:227], v[2:3], v[226:227]
	global_store_dwordx4 v174, v[226:229], s[84:85] offset:576
	v_mul_f32_e32 v178, v229, v229
	v_mul_f32_e32 v177, v227, v227
	v_fmac_f32_e32 v177, v226, v226
	v_fmac_f32_e32 v178, v228, v228
	v_cvt_pk_bf16_f32 v182, v226, v227
	v_cvt_pk_bf16_f32 v183, v228, v229
	v_add_f32_e32 v177, v177, v178
	v_add_f32_e32 v179, v179, v177
	global_store_dwordx2 v175, v[182:183], s[18:19] offset:288
	ds_bpermute_b32 v177, v141, v179
	s_waitcnt lgkmcnt(0)
	v_add_f32_e32 v179, v179, v177
	ds_bpermute_b32 v178, v172, v179
	s_waitcnt lgkmcnt(0)
	v_add_f32_e32 v179, v179, v178
	s_and_saveexec_b64 s[52:53], s[4:5]
	global_store_dword v176, v179, s[14:15]
	s_mov_b64 exec, s[52:53]
	s_and_b64 vcc, exec, s[6:7]
	s_mov_b64 s[6:7], -1
	s_cbranch_vccnz .LBB0_406
	s_andn2_b64 vcc, exec, s[16:17]
	s_cbranch_vccnz .LBB0_405
	s_barrier
	s_branch .LBB0_405
